# NSA step loops: waves 4-7 run QK MFMAs first then exp stream (role split vs waves 0-3), RET K-read hoist, RET pk split
# baseline (speedup 1.0000x reference)
.LBB0_475:
	s_add_i32 s6, s13, 3
	s_cmp_gt_i32 s42, s6
	s_cselect_b64 s[14:15], -1, 0
	s_cmp_ge_i32 s42, s43
	s_waitcnt lgkmcnt(0)
	s_barrier
	s_cselect_b64 s[16:17], -1, 0
	s_cmp_lt_i32 s13, s1
	s_cbranch_scc0 .Lret_nh1
	s_or_b32 s100, s13, 1
	s_lshl_b32 s100, s100, 15
	s_and_b32 s100, s100, 0x18000
	v_or_b32_e32 v138, s100, v209
	v_add_u32_e32 v102, v138, v210
	ds_read_b128 v[98:101], v102
	ds_read_b128 v[102:105], v102 offset:4096
	v_add_u32_e32 v134, v138, v211
	ds_read_b128 v[130:133], v134
	ds_read_b128 v[134:137], v134 offset:4096
.Lret_nh1:
	s_or_b64 s[14:15], s[16:17], s[14:15]
	s_and_b64 vcc, exec, s[14:15]
	s_cbranch_vccnz .LBB0_478
	s_lshl_b32 s7, s42, 6
	s_lshl_b32 s12, s42, 15
.LBB0_477:
	s_and_b32 s16, s12, 0x18000
	s_mul_i32 s18, s7, 0x3000
	v_mad_i64_i32 v[252:253], s[14:15], s7, v229, v[196:197]
	s_add_i32 s16, s29, s16
	s_mul_hi_i32 s17, s7, 0x3000
	s_add_u32 s14, s4, s18
	s_mov_b32 m0, s16
	s_addc_u32 s15, s5, s17
	global_load_lds_dwordx4 v[252:253], off
	s_add_i32 m0, s16, 0x4000
	v_lshl_add_u64 v[252:253], s[14:15], 0, v[206:207]
	global_load_lds_dwordx4 v[252:253], off
	v_lshl_add_u64 v[252:253], v[252:253], 0, s[86:87]
	s_add_i32 m0, s16, 0x6000
	s_mov_b32 s14, s42
	global_load_lds_dwordx4 v[252:253], off
	s_add_i32 s42, s42, 1
	s_cmp_lt_i32 s14, s6
	s_cselect_b64 s[14:15], -1, 0
	s_cmp_lt_i32 s42, s43
	s_cselect_b64 s[16:17], -1, 0
	s_and_b64 s[14:15], s[14:15], s[16:17]
	s_add_i32 s7, s7, 64
	s_add_i32 s12, s12, 0x8000
	s_and_b64 vcc, exec, s[14:15]
	s_cbranch_vccnz .LBB0_477
.LBB0_478:
	s_or_b32 s12, s13, 1
	s_cmp_gt_i32 s13, s1
	s_cbranch_scc1 .LBB0_484
	s_lshl_b32 s6, s13, 6
	v_subrev_u32_e32 v252, s6, v178
	v_cvt_f32_i32_e32 v252, v252
	s_mov_b64 s[6:7], -1
	s_cmp_ge_i32 s13, s1
	v_mul_f32_e32 v252, v201, v252
	v_exp_f32_e32 v200, v252
	s_nop 0
	v_mul_f32_e32 v198, v202, v200
	s_cbranch_scc0 .LBB0_481
	v_mov_b32_e32 v224, v205
	v_pk_mul_f32 v[130:131], v[184:185], v[200:201] op_sel_hi:[1,0]
	v_pk_mul_f32 v[138:139], v[192:193], v[200:201] op_sel_hi:[1,0]
	v_pk_mul_f32 v[144:145], v[194:195], v[200:201] op_sel_hi:[1,0]
	v_pk_mul_f32 v[150:151], v[88:89], v[138:139]
	v_pk_mul_f32 v[138:139], v[96:97], v[130:131]
	v_pk_mul_f32 v[130:131], v[82:83], v[144:145]
	v_cmp_lt_i32_e32 vcc, 0, v224
	v_pk_mul_f32 v[132:133], v[180:181], v[200:201] op_sel_hi:[1,0]
	v_pk_mul_f32 v[142:143], v[190:191], v[200:201] op_sel_hi:[1,0]
	v_cndmask_b32_e32 v131, 0, v131, vcc
	v_cmp_lt_i32_e32 vcc, -1, v224
	v_pk_mul_f32 v[132:133], v[94:95], v[132:133]
	v_pk_mul_f32 v[134:135], v[182:183], v[200:201] op_sel_hi:[1,0]
	v_cndmask_b32_e32 v130, 0, v130, vcc
	v_cmp_lt_i32_e32 vcc, 26, v224
	v_pk_mul_f32 v[146:147], v[84:85], v[142:143]
	v_pk_mul_f32 v[140:141], v[188:189], v[200:201] op_sel_hi:[1,0]
	v_cndmask_b32_e32 v145, 0, v139, vcc
	v_cmp_lt_i32_e32 vcc, 25, v224
	v_pk_mul_f32 v[134:135], v[92:93], v[134:135]
	v_pk_mul_f32 v[136:137], v[186:187], v[200:201] op_sel_hi:[1,0]
	v_cndmask_b32_e32 v144, 0, v138, vcc
	v_cmp_lt_i32_e32 vcc, 24, v224
	v_pk_mul_f32 v[148:149], v[86:87], v[140:141]
	v_pk_mul_f32 v[136:137], v[90:91], v[136:137]
	v_cndmask_b32_e32 v143, 0, v133, vcc
	v_cmp_lt_i32_e32 vcc, 23, v224
	v_pk_mul_f32 v[160:161], v[194:195], v[198:199] op_sel_hi:[1,0]
	v_pk_mul_f32 v[158:159], v[190:191], v[198:199] op_sel_hi:[1,0]
	v_cndmask_b32_e32 v142, 0, v132, vcc
	v_cmp_lt_i32_e32 vcc, 18, v224
	v_pk_mul_f32 v[220:221], v[160:161], v[66:67]
	v_pk_mul_f32 v[214:215], v[158:159], v[68:69]
	v_cndmask_b32_e32 v141, 0, v135, vcc
	v_cmp_lt_i32_e32 vcc, 17, v224
	v_pk_mul_f32 v[156:157], v[188:189], v[198:199] op_sel_hi:[1,0]
	v_pk_mul_f32 v[152:153], v[186:187], v[198:199] op_sel_hi:[1,0]
	v_cndmask_b32_e32 v140, 0, v134, vcc
	v_cmp_lt_i32_e32 vcc, 16, v224
	v_pk_mul_f32 v[216:217], v[156:157], v[70:71]
	v_pk_mul_f32 v[154:155], v[192:193], v[198:199] op_sel_hi:[1,0]
	v_cndmask_b32_e32 v139, 0, v137, vcc
	v_cmp_lt_i32_e32 vcc, 15, v224
	v_pk_mul_f32 v[152:153], v[152:153], v[74:75]
	v_pk_mul_f32 v[218:219], v[154:155], v[72:73]
	v_cndmask_b32_e32 v138, 0, v136, vcc
	v_cmp_lt_i32_e32 vcc, 10, v224
	s_mov_b64 s[6:7], 0
	s_nop 0
	v_cndmask_b32_e32 v137, 0, v151, vcc
	v_cmp_lt_i32_e32 vcc, 9, v224
	s_nop 1
	v_cndmask_b32_e32 v136, 0, v150, vcc
	v_cmp_lt_i32_e32 vcc, 8, v224
	v_pk_mul_f32 v[150:151], v[182:183], v[198:199] op_sel_hi:[1,0]
	s_nop 0
	v_cndmask_b32_e32 v135, 0, v149, vcc
	v_cmp_lt_i32_e32 vcc, 7, v224
	v_pk_mul_f32 v[150:151], v[150:151], v[76:77]
	s_nop 0
	v_cndmask_b32_e32 v134, 0, v148, vcc
	v_cmp_lt_i32_e32 vcc, 2, v224
	v_pk_mul_f32 v[148:149], v[180:181], v[198:199] op_sel_hi:[1,0]
	s_nop 0
	v_cndmask_b32_e32 v133, 0, v147, vcc
	v_cmp_lt_i32_e32 vcc, 1, v224
	v_pk_mul_f32 v[148:149], v[148:149], v[78:79]
	s_nop 0
	v_cndmask_b32_e32 v132, 0, v146, vcc
	v_pk_mul_f32 v[146:147], v[184:185], v[198:199] op_sel_hi:[1,0]
	v_cmp_lt_i32_e32 vcc, 58, v224
	v_pk_mul_f32 v[146:147], v[146:147], v[80:81]
	s_nop 0
	v_cndmask_b32_e32 v161, 0, v147, vcc
	v_cmp_lt_i32_e32 vcc, 57, v224
	s_nop 1
	v_cndmask_b32_e32 v160, 0, v146, vcc
	v_cmp_lt_i32_e32 vcc, 56, v224
	s_nop 1
	v_cndmask_b32_e32 v159, 0, v149, vcc
	v_cmp_lt_i32_e32 vcc, 55, v224
	s_nop 1
	v_cndmask_b32_e32 v158, 0, v148, vcc
	v_cmp_lt_i32_e32 vcc, 50, v224
	s_nop 1
	v_cndmask_b32_e32 v157, 0, v151, vcc
	v_cmp_lt_i32_e32 vcc, 49, v224
	s_nop 1
	v_cndmask_b32_e32 v156, 0, v150, vcc
	v_cmp_lt_i32_e32 vcc, 48, v224
	s_nop 1
	v_cndmask_b32_e32 v155, 0, v153, vcc
	v_cmp_lt_i32_e32 vcc, 47, v224
	s_nop 1
	v_cndmask_b32_e32 v154, 0, v152, vcc
	v_cmp_lt_i32_e32 vcc, 42, v224
	s_nop 1
	v_cndmask_b32_e32 v153, 0, v219, vcc
	v_cmp_lt_i32_e32 vcc, 41, v224
	s_nop 1
	v_cndmask_b32_e32 v152, 0, v218, vcc
	v_cmp_lt_i32_e32 vcc, 40, v224
	s_nop 1
	v_cndmask_b32_e32 v151, 0, v217, vcc
	v_cmp_lt_i32_e32 vcc, 39, v224
	s_nop 1
	v_cndmask_b32_e32 v150, 0, v216, vcc
	v_cmp_lt_i32_e32 vcc, 34, v224
	s_nop 1
	v_cndmask_b32_e32 v149, 0, v215, vcc
	v_cmp_lt_i32_e32 vcc, 33, v224
	s_nop 1
	v_cndmask_b32_e32 v148, 0, v214, vcc
	v_cmp_lt_i32_e32 vcc, 32, v224
	s_nop 1
	v_cndmask_b32_e32 v147, 0, v221, vcc
	v_cmp_lt_i32_e32 vcc, 31, v224
	s_nop 1
	v_cndmask_b32_e32 v146, 0, v220, vcc
; #define MFMA(a, b, c) __builtin_amdgcn_mfma_f32_32x32x16_f16((a), (b), (c), 0, 0, 0)
; DI void ret_qk_decay(f32x16& n0, f32x16& n1, const char* stg, const f16x8 (&qf)[4], int l31, int h, int xx, f32x16& c0, f32x16& c1, const float (&fac)[16], float base, float e32) {
;   const f32x16 zero = {0.f, 0.f, 0.f, 0.f, 0.f, 0.f, 0.f, 0.f, 0.f, 0.f, 0.f, 0.f, 0.f, 0.f, 0.f, 0.f};
;   const float base1 = base * e32;
; #pragma unroll
;   for (int s = 0; s < 4; ++s) {
;     const unsigned cxs = (unsigned)(((2 * s + h) ^ xx) << 4);
;     const f16x8 k0 = *(const f16x8*)(stg + l31 * 128 + cxs);
;     const f16x8 k1 = *(const f16x8*)(stg + (l31 + 32) * 128 + cxs);
;     n0 = MFMA(k0, qf[s], s == 0 ? zero : n0); n1 = MFMA(k1, qf[s], s == 0 ? zero : n1);
; #pragma unroll
;     for (int j = 0; j < 4; ++j) { const int r = 4 * s + j; c0[r] *= base * fac[r]; c1[r] *= base1 * fac[r]; }
;   }
; }
.LBB0_481:
	s_andn2_b64 vcc, exec, s[6:7]
	s_cbranch_vccnz .LBB0_483
	v_mul_f32_e32 v140, v180, v200
	v_mul_f32_e32 v141, v181, v200
	s_waitcnt lgkmcnt(0)
	v_mfma_f32_32x32x16_f16 v[114:129], v[98:101], v[174:177], 0
	v_mul_f32_e64 v142, v184, v200
	v_mul_f32_e64 v143, v185, v200
	v_mul_f32_e64 v146, v194, v200
	v_mul_f32_e64 v147, v195, v200
	v_mul_f32_e64 v144, v96, v142
	v_mul_f32_e64 v145, v97, v143
	v_mul_f32_e32 v142, v94, v140
	v_mul_f32_e32 v143, v95, v141
	v_mul_f32_e32 v94, v184, v198
	v_mul_f32_e32 v95, v185, v198
	v_mul_f32_e32 v96, v194, v198
	v_mul_f32_e32 v97, v195, v198
	v_mul_f32_e32 v160, v94, v80
	v_mul_f32_e32 v161, v95, v81
	v_mfma_f32_32x32x16_f16 v[98:113], v[102:105], v[174:177], 0
	v_mfma_f32_32x32x16_f16 v[114:129], v[130:133], v[170:173], v[114:129]
	v_mfma_f32_32x32x16_f16 v[98:113], v[134:137], v[170:173], v[98:113]
	v_add_u32_e32 v134, v138, v212
	ds_read_b128 v[130:133], v134
	ds_read_b128 v[134:137], v134 offset:4096
	s_waitcnt lgkmcnt(0)
	v_mfma_f32_32x32x16_f16 v[114:129], v[130:133], v[166:169], v[114:129]
	v_mfma_f32_32x32x16_f16 v[98:113], v[134:137], v[166:169], v[98:113]
	v_add_u32_e32 v134, v138, v213
	ds_read_b128 v[130:133], v134
	ds_read_b128 v[134:137], v134 offset:4096
	v_mul_f32_e64 v138, v182, v200
	v_mul_f32_e64 v139, v183, v200
	v_mul_f32_e32 v140, v92, v138
	v_mul_f32_e32 v141, v93, v139
	v_mul_f32_e32 v92, v180, v198
	v_mul_f32_e32 v93, v181, v198
	s_waitcnt lgkmcnt(0)
	v_mfma_f32_32x32x16_f16 v[114:129], v[130:133], v[162:165], v[114:129]
	v_mul_f32_e64 v130, v190, v200
	v_mul_f32_e64 v131, v191, v200
	v_mul_f32_e64 v132, v188, v200
	v_mul_f32_e64 v133, v189, v200
	v_mul_f32_e64 v158, v92, v78
	v_mul_f32_e64 v159, v93, v79
	v_mfma_f32_32x32x16_f16 v[98:113], v[134:137], v[162:165], v[98:113]
	v_mul_f32_e64 v134, v192, v200
	v_mul_f32_e64 v135, v193, v200
	v_mul_f32_e64 v136, v186, v200
	v_mul_f32_e64 v137, v187, v200
	v_mul_f32_e64 v138, v90, v136
	v_mul_f32_e64 v139, v91, v137
	v_mul_f32_e32 v136, v88, v134
	v_mul_f32_e32 v137, v89, v135
	v_mul_f32_e32 v134, v86, v132
	v_mul_f32_e32 v135, v87, v133
	v_mul_f32_e32 v132, v84, v130
	v_mul_f32_e32 v133, v85, v131
	v_mul_f32_e32 v130, v82, v146
	v_mul_f32_e32 v131, v83, v147
	v_mul_f32_e32 v82, v190, v198
	v_mul_f32_e32 v83, v191, v198
	v_mul_f32_e32 v84, v188, v198
	v_mul_f32_e32 v85, v189, v198
	v_mul_f32_e32 v86, v192, v198
	v_mul_f32_e32 v87, v193, v198
	v_mul_f32_e32 v88, v186, v198
	v_mul_f32_e32 v89, v187, v198
	v_mul_f32_e32 v90, v182, v198
	v_mul_f32_e32 v91, v183, v198
	v_mul_f32_e32 v154, v88, v74
	v_mul_f32_e32 v155, v89, v75
	v_mul_f32_e32 v156, v90, v76
	v_mul_f32_e32 v157, v91, v77
	v_mul_f32_e32 v152, v86, v72
	v_mul_f32_e32 v153, v87, v73
	v_mul_f32_e32 v150, v84, v70
	v_mul_f32_e32 v151, v85, v71
	v_mul_f32_e32 v148, v82, v68
	v_mul_f32_e32 v149, v83, v69
	v_mul_f32_e32 v146, v96, v66
	v_mul_f32_e32 v147, v97, v67

.LBB0_495:
	s_add_i32 s6, s13, 4
	s_cmp_gt_i32 s42, s6
	s_cselect_b64 s[14:15], -1, 0
	s_cmp_ge_i32 s42, s43
	s_waitcnt lgkmcnt(0)
	s_barrier
	s_cselect_b64 s[16:17], -1, 0
	s_cmp_lt_i32 s12, s1
	s_cbranch_scc0 .Lret_nh2
	s_not_b32 s100, s13
	s_lshl_b32 s100, s100, 15
	s_and_b32 s100, s100, 0x10000
	v_or_b32_e32 v138, s100, v209
	v_add_u32_e32 v70, v138, v210
	ds_read_b128 v[66:69], v70
	ds_read_b128 v[70:73], v70 offset:4096
	v_add_u32_e32 v134, v138, v211
	ds_read_b128 v[130:133], v134
	ds_read_b128 v[134:137], v134 offset:4096
.Lret_nh2:
	s_or_b64 s[14:15], s[14:15], s[16:17]
	s_and_b64 vcc, exec, s[14:15]
	s_cbranch_vccnz .LBB0_498
	s_lshl_b32 s7, s42, 6
	s_lshl_b32 s14, s42, 15
.LBB0_497:
	s_and_b32 s15, s14, 0x18000
	s_mul_i32 s19, s7, 0x3000
	v_mad_i64_i32 v[252:253], s[16:17], s7, v229, v[196:197]
	s_add_i32 s15, s29, s15
	s_mul_hi_i32 s18, s7, 0x3000
	s_add_u32 s16, s4, s19
	s_mov_b32 m0, s15
	s_addc_u32 s17, s5, s18
	global_load_lds_dwordx4 v[252:253], off
	s_add_i32 m0, s15, 0x4000
	v_lshl_add_u64 v[252:253], s[16:17], 0, v[206:207]
	global_load_lds_dwordx4 v[252:253], off
	v_lshl_add_u64 v[252:253], v[252:253], 0, s[86:87]
	s_add_i32 m0, s15, 0x6000
	s_mov_b32 s15, s42
	global_load_lds_dwordx4 v[252:253], off
	s_add_i32 s42, s42, 1
	s_cmp_lt_i32 s15, s6
	s_cselect_b64 s[16:17], -1, 0
	s_cmp_lt_i32 s42, s43
	s_cselect_b64 s[18:19], -1, 0
	s_and_b64 s[16:17], s[16:17], s[18:19]
	s_add_i32 s7, s7, 64
	s_add_i32 s14, s14, 0x8000
	s_and_b64 vcc, exec, s[16:17]
	s_cbranch_vccnz .LBB0_497
.LBB0_498:
	s_cmp_ge_i32 s13, s1
	s_cbranch_scc1 .LBB0_504
	s_lshl_b32 s6, s12, 6
	v_subrev_u32_e32 v252, s6, v178
	v_cvt_f32_i32_e32 v252, v252
	s_mov_b64 s[6:7], -1
	s_cmp_ge_i32 s12, s1
	v_mul_f32_e32 v252, v201, v252
	v_exp_f32_e32 v200, v252
	s_nop 0
	v_mul_f32_e32 v198, v202, v200
	s_cbranch_scc0 .LBB0_501
	v_mov_b32_e32 v224, v205
	v_pk_mul_f32 v[130:131], v[184:185], v[200:201] op_sel_hi:[1,0]
	v_pk_mul_f32 v[138:139], v[192:193], v[200:201] op_sel_hi:[1,0]
	v_pk_mul_f32 v[144:145], v[194:195], v[200:201] op_sel_hi:[1,0]
	v_pk_mul_f32 v[150:151], v[138:139], v[120:121]
	v_pk_mul_f32 v[138:139], v[130:131], v[128:129]
	v_pk_mul_f32 v[130:131], v[144:145], v[114:115]
	v_cmp_lt_i32_e32 vcc, 0, v224
	v_pk_mul_f32 v[132:133], v[180:181], v[200:201] op_sel_hi:[1,0]
	v_pk_mul_f32 v[142:143], v[190:191], v[200:201] op_sel_hi:[1,0]
	v_cndmask_b32_e32 v131, 0, v131, vcc
	v_cmp_lt_i32_e32 vcc, -1, v224
	v_pk_mul_f32 v[132:133], v[132:133], v[126:127]
	v_pk_mul_f32 v[134:135], v[182:183], v[200:201] op_sel_hi:[1,0]
	v_cndmask_b32_e32 v130, 0, v130, vcc
	v_cmp_lt_i32_e32 vcc, 26, v224
	v_pk_mul_f32 v[146:147], v[142:143], v[116:117]
	v_pk_mul_f32 v[140:141], v[188:189], v[200:201] op_sel_hi:[1,0]
	v_cndmask_b32_e32 v145, 0, v139, vcc
	v_cmp_lt_i32_e32 vcc, 25, v224
	v_pk_mul_f32 v[134:135], v[134:135], v[124:125]
	v_pk_mul_f32 v[136:137], v[186:187], v[200:201] op_sel_hi:[1,0]
	v_cndmask_b32_e32 v144, 0, v138, vcc
	v_cmp_lt_i32_e32 vcc, 24, v224
	v_pk_mul_f32 v[148:149], v[140:141], v[118:119]
	v_pk_mul_f32 v[136:137], v[136:137], v[122:123]
	v_cndmask_b32_e32 v143, 0, v133, vcc
	v_cmp_lt_i32_e32 vcc, 23, v224
	v_pk_mul_f32 v[160:161], v[194:195], v[198:199] op_sel_hi:[1,0]
	v_pk_mul_f32 v[158:159], v[190:191], v[198:199] op_sel_hi:[1,0]
	v_cndmask_b32_e32 v142, 0, v132, vcc
	v_cmp_lt_i32_e32 vcc, 18, v224
	v_pk_mul_f32 v[220:221], v[160:161], v[98:99]
	v_pk_mul_f32 v[214:215], v[158:159], v[100:101]
	v_cndmask_b32_e32 v141, 0, v135, vcc
	v_cmp_lt_i32_e32 vcc, 17, v224
	v_pk_mul_f32 v[156:157], v[188:189], v[198:199] op_sel_hi:[1,0]
	v_pk_mul_f32 v[152:153], v[186:187], v[198:199] op_sel_hi:[1,0]
	v_cndmask_b32_e32 v140, 0, v134, vcc
	v_cmp_lt_i32_e32 vcc, 16, v224
	v_pk_mul_f32 v[216:217], v[156:157], v[102:103]
	v_pk_mul_f32 v[154:155], v[192:193], v[198:199] op_sel_hi:[1,0]
	v_cndmask_b32_e32 v139, 0, v137, vcc
	v_cmp_lt_i32_e32 vcc, 15, v224
	v_pk_mul_f32 v[152:153], v[152:153], v[106:107]
	v_pk_mul_f32 v[218:219], v[154:155], v[104:105]
	v_cndmask_b32_e32 v138, 0, v136, vcc
	v_cmp_lt_i32_e32 vcc, 10, v224
	s_mov_b64 s[6:7], 0
	s_nop 0
	v_cndmask_b32_e32 v137, 0, v151, vcc
	v_cmp_lt_i32_e32 vcc, 9, v224
	s_nop 1
	v_cndmask_b32_e32 v136, 0, v150, vcc
	v_cmp_lt_i32_e32 vcc, 8, v224
	v_pk_mul_f32 v[150:151], v[182:183], v[198:199] op_sel_hi:[1,0]
	s_nop 0
	v_cndmask_b32_e32 v135, 0, v149, vcc
	v_cmp_lt_i32_e32 vcc, 7, v224
	v_pk_mul_f32 v[150:151], v[150:151], v[108:109]
	s_nop 0
	v_cndmask_b32_e32 v134, 0, v148, vcc
	v_cmp_lt_i32_e32 vcc, 2, v224
	v_pk_mul_f32 v[148:149], v[180:181], v[198:199] op_sel_hi:[1,0]
	s_nop 0
	v_cndmask_b32_e32 v133, 0, v147, vcc
	v_cmp_lt_i32_e32 vcc, 1, v224
	v_pk_mul_f32 v[148:149], v[148:149], v[110:111]
	s_nop 0
	v_cndmask_b32_e32 v132, 0, v146, vcc
	v_pk_mul_f32 v[146:147], v[184:185], v[198:199] op_sel_hi:[1,0]
	v_cmp_lt_i32_e32 vcc, 58, v224
	v_pk_mul_f32 v[146:147], v[146:147], v[112:113]
	s_nop 0
	v_cndmask_b32_e32 v161, 0, v147, vcc
	v_cmp_lt_i32_e32 vcc, 57, v224
	s_nop 1
	v_cndmask_b32_e32 v160, 0, v146, vcc
	v_cmp_lt_i32_e32 vcc, 56, v224
	s_nop 1
	v_cndmask_b32_e32 v159, 0, v149, vcc
	v_cmp_lt_i32_e32 vcc, 55, v224
	s_nop 1
	v_cndmask_b32_e32 v158, 0, v148, vcc
	v_cmp_lt_i32_e32 vcc, 50, v224
	s_nop 1
	v_cndmask_b32_e32 v157, 0, v151, vcc
	v_cmp_lt_i32_e32 vcc, 49, v224
	s_nop 1
	v_cndmask_b32_e32 v156, 0, v150, vcc
	v_cmp_lt_i32_e32 vcc, 48, v224
	s_nop 1
	v_cndmask_b32_e32 v155, 0, v153, vcc
	v_cmp_lt_i32_e32 vcc, 47, v224
	s_nop 1
	v_cndmask_b32_e32 v154, 0, v152, vcc
	v_cmp_lt_i32_e32 vcc, 42, v224
	s_nop 1
	v_cndmask_b32_e32 v153, 0, v219, vcc
	v_cmp_lt_i32_e32 vcc, 41, v224
	s_nop 1
	v_cndmask_b32_e32 v152, 0, v218, vcc
	v_cmp_lt_i32_e32 vcc, 40, v224
	s_nop 1
	v_cndmask_b32_e32 v151, 0, v217, vcc
	v_cmp_lt_i32_e32 vcc, 39, v224
	s_nop 1
	v_cndmask_b32_e32 v150, 0, v216, vcc
	v_cmp_lt_i32_e32 vcc, 34, v224
	s_nop 1
	v_cndmask_b32_e32 v149, 0, v215, vcc
	v_cmp_lt_i32_e32 vcc, 33, v224
	s_nop 1
	v_cndmask_b32_e32 v148, 0, v214, vcc
	v_cmp_lt_i32_e32 vcc, 32, v224
	s_nop 1
	v_cndmask_b32_e32 v147, 0, v221, vcc
	v_cmp_lt_i32_e32 vcc, 31, v224
	s_nop 1
	v_cndmask_b32_e32 v146, 0, v220, vcc
; #define MFMA(a, b, c) __builtin_amdgcn_mfma_f32_32x32x16_f16((a), (b), (c), 0, 0, 0)
; DI void ret_qk_decay(f32x16& n0, f32x16& n1, const char* stg, const f16x8 (&qf)[4], int l31, int h, int xx, f32x16& c0, f32x16& c1, const float (&fac)[16], float base, float e32) {
;   const f32x16 zero = {0.f, 0.f, 0.f, 0.f, 0.f, 0.f, 0.f, 0.f, 0.f, 0.f, 0.f, 0.f, 0.f, 0.f, 0.f, 0.f};
;   const float base1 = base * e32;
; #pragma unroll
;   for (int s = 0; s < 4; ++s) {
;     const unsigned cxs = (unsigned)(((2 * s + h) ^ xx) << 4);
;     const f16x8 k0 = *(const f16x8*)(stg + l31 * 128 + cxs);
;     const f16x8 k1 = *(const f16x8*)(stg + (l31 + 32) * 128 + cxs);
;     n0 = MFMA(k0, qf[s], s == 0 ? zero : n0); n1 = MFMA(k1, qf[s], s == 0 ? zero : n1);
; #pragma unroll
;     for (int j = 0; j < 4; ++j) { const int r = 4 * s + j; c0[r] *= base * fac[r]; c1[r] *= base1 * fac[r]; }
;   }
; }
.LBB0_501:
	s_andn2_b64 vcc, exec, s[6:7]
	s_cbranch_vccnz .LBB0_503
	v_mul_f32_e32 v140, v180, v200
	v_mul_f32_e32 v141, v181, v200
	s_waitcnt lgkmcnt(0)
	v_mfma_f32_32x32x16_f16 v[82:97], v[66:69], v[174:177], 0
	v_mul_f32_e64 v142, v184, v200
	v_mul_f32_e64 v143, v185, v200
	v_mul_f32_e64 v146, v194, v200
	v_mul_f32_e64 v147, v195, v200
	v_mul_f32_e64 v144, v142, v128
	v_mul_f32_e64 v145, v143, v129
	v_mul_f32_e32 v142, v140, v126
	v_mul_f32_e32 v143, v141, v127
	v_mul_f32_e32 v126, v184, v198
	v_mul_f32_e32 v127, v185, v198
	v_mul_f32_e32 v128, v194, v198
	v_mul_f32_e32 v129, v195, v198
	v_mul_f32_e32 v160, v126, v112
	v_mul_f32_e32 v161, v127, v113
	v_mfma_f32_32x32x16_f16 v[66:81], v[70:73], v[174:177], 0
	v_mfma_f32_32x32x16_f16 v[82:97], v[130:133], v[170:173], v[82:97]
	v_mfma_f32_32x32x16_f16 v[66:81], v[134:137], v[170:173], v[66:81]
	v_add_u32_e32 v134, v138, v212
	ds_read_b128 v[130:133], v134
	ds_read_b128 v[134:137], v134 offset:4096
	s_waitcnt lgkmcnt(0)
	v_mfma_f32_32x32x16_f16 v[82:97], v[130:133], v[166:169], v[82:97]
	v_mfma_f32_32x32x16_f16 v[66:81], v[134:137], v[166:169], v[66:81]
	v_add_u32_e32 v134, v138, v213
	ds_read_b128 v[130:133], v134
	ds_read_b128 v[134:137], v134 offset:4096
	v_mul_f32_e64 v138, v182, v200
	v_mul_f32_e64 v139, v183, v200
	v_mul_f32_e32 v140, v138, v124
	v_mul_f32_e32 v141, v139, v125
	v_mul_f32_e32 v124, v180, v198
	v_mul_f32_e32 v125, v181, v198
	s_waitcnt lgkmcnt(0)
	v_mfma_f32_32x32x16_f16 v[82:97], v[130:133], v[162:165], v[82:97]
	v_mul_f32_e64 v130, v190, v200
	v_mul_f32_e64 v131, v191, v200
	v_mul_f32_e64 v132, v188, v200
	v_mul_f32_e64 v133, v189, v200
	v_mul_f32_e64 v158, v124, v110
	v_mul_f32_e64 v159, v125, v111
	v_mfma_f32_32x32x16_f16 v[66:81], v[134:137], v[162:165], v[66:81]
	v_mul_f32_e64 v134, v192, v200
	v_mul_f32_e64 v135, v193, v200
	v_mul_f32_e64 v136, v186, v200
	v_mul_f32_e64 v137, v187, v200
	v_mul_f32_e64 v138, v136, v122
	v_mul_f32_e64 v139, v137, v123
	v_mul_f32_e32 v136, v134, v120
	v_mul_f32_e32 v137, v135, v121
	v_mul_f32_e32 v134, v132, v118
	v_mul_f32_e32 v135, v133, v119
	v_mul_f32_e32 v132, v130, v116
	v_mul_f32_e32 v133, v131, v117
	v_mul_f32_e32 v130, v146, v114
	v_mul_f32_e32 v131, v147, v115
	v_mul_f32_e32 v114, v190, v198
	v_mul_f32_e32 v115, v191, v198
	v_mul_f32_e32 v116, v188, v198
	v_mul_f32_e32 v117, v189, v198
	v_mul_f32_e32 v118, v192, v198
	v_mul_f32_e32 v119, v193, v198
	v_mul_f32_e32 v120, v186, v198
	v_mul_f32_e32 v121, v187, v198
	v_mul_f32_e32 v122, v182, v198
	v_mul_f32_e32 v123, v183, v198
	v_mul_f32_e32 v154, v120, v106
	v_mul_f32_e32 v155, v121, v107
	v_mul_f32_e32 v156, v122, v108
	v_mul_f32_e32 v157, v123, v109
	v_mul_f32_e32 v152, v118, v104
	v_mul_f32_e32 v153, v119, v105
	v_mul_f32_e32 v150, v116, v102
	v_mul_f32_e32 v151, v117, v103
	v_mul_f32_e32 v148, v114, v100
	v_mul_f32_e32 v149, v115, v101
	v_mul_f32_e32 v146, v128, v98
	v_mul_f32_e32 v147, v129, v99

; #define MFMA(a, b, c) __builtin_amdgcn_mfma_f32_32x32x16_f16((a), (b), (c), 0, 0, 0)
; DI void ret_qk_decay(f32x16& n0, f32x16& n1, const char* stg, const f16x8 (&qf)[4], int l31, int h, int xx, f32x16& c0, f32x16& c1, const float (&fac)[16], float base, float e32) {
;   const f32x16 zero = {0.f, 0.f, 0.f, 0.f, 0.f, 0.f, 0.f, 0.f, 0.f, 0.f, 0.f, 0.f, 0.f, 0.f, 0.f, 0.f};
;   const float base1 = base * e32;
; #pragma unroll
;   for (int s = 0; s < 4; ++s) {
;     const unsigned cxs = (unsigned)(((2 * s + h) ^ xx) << 4);
;     const f16x8 k0 = *(const f16x8*)(stg + l31 * 128 + cxs);
;     const f16x8 k1 = *(const f16x8*)(stg + (l31 + 32) * 128 + cxs);
;     n0 = MFMA(k0, qf[s], s == 0 ? zero : n0); n1 = MFMA(k1, qf[s], s == 0 ? zero : n1);
; #pragma unroll
;     for (int j = 0; j < 4; ++j) { const int r = 4 * s + j; c0[r] *= base * fac[r]; c1[r] *= base1 * fac[r]; }
;   }
; }
; DI void ret_unit(const Params& p, int b, int hr, int tq, char* smem) {
;     ...
;   if (kt + 1 < ntile) { RET_BODY(c0, c1, x0, x1); c0 = x0; c1 = x1; ++kt; }
.LBB0_525:
	s_andn2_b64 vcc, exec, s[4:5]
	s_cbranch_vccnz .LBB0_527
	s_lshl_b32 s4, s12, 15
	s_and_b32 s4, s4, 0x18000
	v_or_b32_e32 v138, s4, v209
	v_add_u32_e32 v102, v138, v210
	ds_read_b128 v[98:101], v102
	ds_read_b128 v[102:105], v102 offset:4096
	v_add_u32_e32 v134, v138, v211
	ds_read_b128 v[130:133], v134
	ds_read_b128 v[134:137], v134 offset:4096
	v_mul_f32_e32 v140, v182, v198
	v_mul_f32_e32 v141, v183, v198
	s_waitcnt lgkmcnt(0)
	v_mfma_f32_32x32x16_f16 v[114:129], v[98:101], v[174:177], 0
	v_mul_f32_e64 v142, v180, v198
	v_mul_f32_e64 v143, v181, v198
	v_mul_f32_e64 v144, v184, v198
	v_mul_f32_e64 v145, v185, v198
	v_mul_f32_e64 v142, v94, v142
	v_mul_f32_e64 v143, v95, v143
	v_mul_f32_e32 v144, v96, v144
	v_mul_f32_e32 v145, v97, v145
	v_mul_f32_e32 v140, v92, v140
	v_mul_f32_e32 v141, v93, v141
	v_mul_f32_e32 v92, v182, v196
	v_mul_f32_e32 v93, v183, v196
	v_mul_f32_e32 v94, v180, v196
	v_mul_f32_e32 v95, v181, v196
	v_mfma_f32_32x32x16_f16 v[98:113], v[102:105], v[174:177], 0
	v_mul_f32_e64 v96, v184, v196
	v_mul_f32_e64 v97, v185, v196
	v_mul_f32_e64 v158, v78, v94
	v_mul_f32_e64 v159, v79, v95
	v_mul_f32_e64 v160, v80, v96
	v_mul_f32_e64 v161, v81, v97
	v_mul_f32_e32 v156, v76, v92
	v_mul_f32_e32 v157, v77, v93
	v_mfma_f32_32x32x16_f16 v[114:129], v[130:133], v[170:173], v[114:129]
	v_mfma_f32_32x32x16_f16 v[98:113], v[134:137], v[170:173], v[98:113]
	v_add_u32_e32 v134, v138, v212
	ds_read_b128 v[130:133], v134
	ds_read_b128 v[134:137], v134 offset:4096
	s_waitcnt lgkmcnt(0)
	v_mfma_f32_32x32x16_f16 v[114:129], v[130:133], v[166:169], v[114:129]
	v_mfma_f32_32x32x16_f16 v[98:113], v[134:137], v[166:169], v[98:113]
	v_add_u32_e32 v134, v138, v213
	ds_read_b128 v[130:133], v134
	ds_read_b128 v[134:137], v134 offset:4096
	v_mul_f32_e64 v138, v186, v198
	v_mul_f32_e64 v139, v187, v198
	v_mul_f32_e32 v138, v90, v138
	v_mul_f32_e32 v139, v91, v139
	v_mul_f32_e32 v90, v186, v196
	v_mul_f32_e32 v91, v187, v196
	s_waitcnt lgkmcnt(0)
	v_mfma_f32_32x32x16_f16 v[114:129], v[130:133], v[162:165], v[114:129]
	v_mul_f32_e64 v130, v194, v198
	v_mul_f32_e64 v131, v195, v198
	v_mul_f32_e64 v132, v190, v198
	v_mul_f32_e64 v133, v191, v198
	v_mul_f32_e64 v130, v82, v130
	v_mul_f32_e64 v131, v83, v131
	v_mul_f32_e32 v132, v84, v132
	v_mul_f32_e32 v133, v85, v133
	v_mul_f32_e32 v82, v194, v196
	v_mul_f32_e32 v83, v195, v196
	v_mul_f32_e32 v84, v190, v196
	v_mul_f32_e32 v85, v191, v196
	v_mul_f32_e32 v154, v74, v90
	v_mul_f32_e32 v155, v75, v91
	v_mfma_f32_32x32x16_f16 v[98:113], v[134:137], v[162:165], v[98:113]
	v_mul_f32_e64 v134, v188, v198
	v_mul_f32_e64 v135, v189, v198
	v_mul_f32_e64 v136, v192, v198
	v_mul_f32_e64 v137, v193, v198
	v_mul_f32_e64 v134, v86, v134
	v_mul_f32_e64 v135, v87, v135
	v_mul_f32_e32 v136, v88, v136
	v_mul_f32_e32 v137, v89, v137
	v_mul_f32_e32 v86, v188, v196
	v_mul_f32_e32 v87, v189, v196
	v_mul_f32_e32 v88, v192, v196
	v_mul_f32_e32 v89, v193, v196
	v_mul_f32_e32 v150, v70, v86
	v_mul_f32_e32 v151, v71, v87
	v_mul_f32_e32 v152, v72, v88
	v_mul_f32_e32 v153, v73, v89
	v_mul_f32_e32 v148, v68, v84
	v_mul_f32_e32 v149, v69, v85
	v_mul_f32_e32 v146, v66, v82
	v_mul_f32_e32 v147, v67, v83

; #define LAS __attribute__((address_space(3)))
; DI void glds16(const char* g, LAS unsigned char* l) { __builtin_amdgcn_global_load_lds((const unsigned*)g, (LAS unsigned*)l, 16, 0, 0); }
; DI void nsa_unit(const Params& p, int b, int g, int qt, char* smem) {
;   const int wid = __builtin_amdgcn_readfirstlane(threadIdx.x >> 6);
;   int tid_ = threadIdx.x; asm volatile("" : "+v"(tid_)); const int tid = tid_, lane = tid & 63, l31 = lane & 31, h = lane >> 5;
;   const int tl = 8 * wid + (l31 >> 2), rr = l31 & 3, head = 4 * g + rr;
;   const int t = 64 * qt + tl;
;   const unsigned row = (unsigned)(b * NT + t);
;   char* Zc = p.ws + WS_Z;
;   LAS unsigned char* lds = (LAS unsigned char*)smem;
;   const unsigned ldsw = (unsigned)wid * 1024u;
;   const char* KC = p.ws + WS_KC + (size_t)((b * 2 + g) * 128) * 256;
;   const char* VC = KC + (size_t)4096 * 256;
;   const unsigned cvo = dma_voff128(wid, lane, 256), zvo = dma_voff128(wid, lane, ZW * 2);
;   const char* Zb = Zc + (size_t)b * NT * ZW * 2;
;   const int cKs = ZC_KV + 512 + g * 128, cVs = ZC_KV + 768 + g * 128, cKw = ZC_KV + 1024 + g * 128, cVw = ZC_KV + 1280 + g * 128;
;   const int nwin = (qt >= 8) ? 9 : (qt + 1);
;   const int NTILE = 3 + qt + nwin;
;     ...
;   f16x8 qf[8];
;   LAS unsigned char* qst = lds + (unsigned)(2 + (wid >> 2)) * 32768u + (unsigned)(wid & 3) * 8192u;
;   {
;     const unsigned qsrc0 = ((unsigned)(b * NT + 64 * qt + 8 * wid) * (unsigned)ZW + (unsigned)(ZC_QN + 4 * g * 128)) * 2u;
;     const int hc = lane >> 4, jc = lane & 15;
; #pragma unroll
;     for (int i = 0; i < 8; ++i) {
;       const unsigned kq = (unsigned)(((i & 3) << 2) | hc);
;       glds16(Zc + (size_t)(qsrc0 + (unsigned)i * (unsigned)(ZW * 2) + (((unsigned)hc * 16u + ((unsigned)jc ^ kq)) << 4)), qst + i * 1024);
;     }
;   }
;   f32x4 rt[4];
;   { const float* rp = (const float*)(p.ws + WS_ROT) + (size_t)row * 96 + 16 * h;
; #pragma unroll
;     for (int i = 0; i < 4; ++i) rt[i] = *(const f32x4*)(rp + 4 * i); }
;   float g0, g1, g2;
;   { const float* gp = (const float*)(p.ws + WS_GATES) + (size_t)(row * 24u + head); g0 = gp[0]; g1 = gp[8]; g2 = gp[16]; }
;   wait_count((unsigned*)(p.ws + WS_CTR) + 64 + b, 2u);
.LBB0_533:
	s_and_b64 vcc, exec, s[0:1]
	s_cbranch_vccz .LBB0_342
	v_readfirstlane_b32 s0, v0
	s_lshr_b32 s101, s0, 8
	s_lshr_b32 s40, s44, 1
	s_lshr_b32 s12, s0, 6
	s_lshr_b32 s5, s0, 8
	s_lshl_b32 s0, s0, 7
	s_lshl_b32 s8, s62, 6
	s_lshl_b32 s4, s40, 11
	v_writelane_b32 v255, s5, 40
	s_lshl_b32 s5, s5, 15
	s_and_b32 s0, s0, 0x6000
	v_mov_b32_e32 v92, v0
	s_lshl_b32 s1, s12, 3
	v_writelane_b32 v255, s0, 41
	s_or_b32 s0, s5, s0
	s_add_i32 s5, s8, s4
	s_and_b32 s3, s44, 1
	s_add_i32 s5, s5, s1
	v_bfe_u32 v183, v92, 4, 2
	s_mulk_i32 s5, 0x1800
	s_lshl_b32 s6, s3, 9
	v_and_b32_e32 v2, 48, v92
	v_bitop3_b32 v184, v183, v92, 15 bitop3:0x78
	s_or_b32 s5, s5, s6
	v_or_b32_e32 v3, v184, v2
	s_add_i32 s9, s0, 0x10000
	s_lshl_b32 s72, s5, 1
	v_and_b32_e32 v93, 15, v92
	v_lshlrev_b32_e32 v3, 4, v3
	v_or_b32_e32 v4, s72, v3
	s_mov_b32 m0, s9
	v_bitop3_b32 v182, v183, v93, 4 bitop3:0x36
	global_load_lds_dwordx4 v4, s[70:71]
	v_or_b32_e32 v4, v182, v2
	v_lshlrev_b32_e32 v4, 4, v4
	v_or_b32_e32 v5, s72, v4
	v_or_b32_e32 v5, 0x3000, v5
	s_add_i32 m0, s0, 0x10400
	s_add_i32 s5, s72, 0x9000
	global_load_lds_dwordx4 v5, s[70:71]
	v_bitop3_b32 v5, v183, v93, 8 bitop3:0x36
	v_or_b32_e32 v5, v5, v2
	v_lshlrev_b32_e32 v5, 4, v5
	v_or_b32_e32 v6, s72, v5
	v_or_b32_e32 v6, 0x6000, v6
	s_add_i32 m0, s0, 0x10800
	v_bfe_u32 v104, v92, 2, 3
	global_load_lds_dwordx4 v6, s[70:71]
	v_bitop3_b32 v6, v183, v93, 12 bitop3:0x36
	v_or_b32_e32 v2, v6, v2
	v_lshlrev_b32_e32 v2, 4, v2
	v_or_b32_e32 v6, s5, v2
	s_add_i32 m0, s0, 0x10c00
	s_add_i32 s5, s72, 0xc000
	global_load_lds_dwordx4 v6, s[70:71]
	v_or_b32_e32 v3, s5, v3
	s_add_i32 m0, s0, 0x11000
	s_add_i32 s5, s72, 0xf000
	global_load_lds_dwordx4 v3, s[70:71]
	v_or_b32_e32 v3, s5, v4
	s_add_i32 m0, s0, 0x11400
	s_add_i32 s5, s72, 0x12000
	global_load_lds_dwordx4 v3, s[70:71]
	v_or_b32_e32 v3, s5, v5
	s_add_i32 m0, s0, 0x11800
	s_add_i32 s5, s72, 0x15000
	global_load_lds_dwordx4 v3, s[70:71]
	s_add_i32 m0, s0, 0x11c00
	v_or_b32_e32 v67, s1, v104
	v_readlane_b32 s0, v255, 13
	v_or_b32_e32 v2, s5, v2
	v_add_u32_e32 v68, s8, v67
	v_readlane_b32 s1, v255, 14
	global_load_lds_dwordx4 v2, s[70:71]
	v_add_u32_e32 v18, s4, v68
	v_mov_b64_e32 v[2:3], s[0:1]
	s_movk_i32 s0, 0x180
	v_bfe_u32 v185, v92, 5, 1
	v_mad_u64_u32 v[2:3], s[0:1], v18, s0, v[2:3]
	v_and_b32_e32 v1, 3, v92
	v_lshlrev_b32_e32 v206, 6, v185
	s_lshl_b32 s0, s3, 2
	v_mul_lo_u32 v18, v18, 24
	v_lshl_add_u64 v[14:15], v[2:3], 0, v[206:207]
	v_or3_b32 v206, v18, s0, v1
	v_readlane_b32 s0, v255, 11
	v_readlane_b32 s1, v255, 12
	global_load_dwordx4 v[2:5], v[14:15], off offset:48
	global_load_dwordx4 v[6:9], v[14:15], off offset:32
	global_load_dwordx4 v[10:13], v[14:15], off offset:16
	s_nop 0
	global_load_dwordx4 v[14:17], v[14:15], off
	v_lshl_add_u64 v[18:19], v[206:207], 2, s[0:1]
	global_load_dword v66, v[18:19], off
	global_load_dword v191, v[18:19], off offset:32
	global_load_dword v187, v[18:19], off offset:64
	s_and_saveexec_b64 s[0:1], s[10:11]
	s_cbranch_execz .LBB0_549
	s_lshl_b64 s[4:5], s[40:41], 2
	v_readlane_b32 s6, v255, 28
	s_add_u32 s4, s6, s4
	v_readlane_b32 s6, v255, 29
	s_addc_u32 s5, s6, s5
	s_mov_b32 s13, 0x1000000
	s_branch .LBB0_538

; #define MFMA(a, b, c) __builtin_amdgcn_mfma_f32_32x32x16_f16((a), (b), (c), 0, 0, 0)
; #define QK_LD(dst, s0) do { dst[0] = *(const f16x8*)(Kst + kbe + 512 * ((s0) >> 1)); dst[1] = *(const f16x8*)(Kst + kbe + 512 * ((s0) >> 1) + 8192); \
;     dst[2] = *(const f16x8*)(Kst + kbo + 512 * ((s0) >> 1)); dst[3] = *(const f16x8*)(Kst + kbo + 512 * ((s0) >> 1) + 8192); } while (0)
; #define QK_LD(dst, s0) do { dst[0] = *(const f16x8*)(Kst + kbe + 512 * ((s0) >> 1)); dst[1] = *(const f16x8*)(Kst + kbe + 512 * ((s0) >> 1) + 8192); \
;     dst[2] = *(const f16x8*)(Kst + kbo + 512 * ((s0) >> 1)); dst[3] = *(const f16x8*)(Kst + kbo + 512 * ((s0) >> 1) + 8192); } while (0)
; #define EXP8(c, b0) do { _Pragma("unroll") for (int j_ = 0; j_ < 8; ++j_) { c[(b0) + j_] = fexp2(c[(b0) + j_] - me); s_ += c[(b0) + j_]; } } while (0)
; DI void qk_exp(f32x16& n0, f32x16& n1, const char* Kst, const f16x8 (&qf)[8], unsigned kbe, unsigned kbo, f32x16& c0, f32x16& c1, float me, float& ps) {
;   const f32x16 zero = {0.f, 0.f, 0.f, 0.f, 0.f, 0.f, 0.f, 0.f, 0.f, 0.f, 0.f, 0.f, 0.f, 0.f, 0.f, 0.f};
;   f16x8 ka[4], kb[4];
;     ...
;   float s_ = 0.f;
;   QK_LD(ka, 0);
;   n0 = MFMA(ka[0], qf[0], zero); n1 = MFMA(ka[1], qf[0], zero); n0 = MFMA(ka[2], qf[1], n0); n1 = MFMA(ka[3], qf[1], n1);
;   QK_LD(kb, 2);
;   EXP8(c0, 0);
;   n0 = MFMA(kb[0], qf[2], n0); n1 = MFMA(kb[1], qf[2], n1); n0 = MFMA(kb[2], qf[3], n0); n1 = MFMA(kb[3], qf[3], n1);
;   QK_LD(ka, 4);
;   EXP8(c0, 8);
;   n0 = MFMA(ka[0], qf[4], n0); n1 = MFMA(ka[1], qf[4], n1); n0 = MFMA(ka[2], qf[5], n0); n1 = MFMA(ka[3], qf[5], n1);
;   QK_LD(kb, 6);
;   EXP8(c1, 0);
;   n0 = MFMA(kb[0], qf[6], n0); n1 = MFMA(kb[1], qf[6], n1); n0 = MFMA(kb[2], qf[7], n0); n1 = MFMA(kb[3], qf[7], n1);
;   EXP8(c1, 8);
;   ps = s_;
;     ...
; }
.Lnsa_b1:
	ds_read_b128 v[240:243], v205 offset:512
	ds_read_b128 v[244:247], v205 offset:8704
	ds_read_b128 v[208:211], v216 offset:512
	ds_read_b128 v[212:215], v216 offset:8704
	s_waitcnt lgkmcnt(4)
	v_mfma_f32_32x32x16_f16 v[114:129], v[98:101], v[150:153], 0
	v_mfma_f32_32x32x16_f16 v[98:113], v[102:105], v[150:153], 0
	v_mfma_f32_32x32x16_f16 v[114:129], v[196:199], v[158:161], v[114:129]
	v_mfma_f32_32x32x16_f16 v[98:113], v[200:203], v[158:161], v[98:113]
	ds_read_b128 v[248:251], v205 offset:1024
	ds_read_b128 v[218:221], v205 offset:9216
	ds_read_b128 v[196:199], v216 offset:1024
	ds_read_b128 v[200:203], v216 offset:9216
	s_waitcnt lgkmcnt(4)
	v_mfma_f32_32x32x16_f16 v[114:129], v[240:243], v[142:145], v[114:129]
	v_mfma_f32_32x32x16_f16 v[98:113], v[244:247], v[142:145], v[98:113]
	v_mfma_f32_32x32x16_f16 v[114:129], v[208:211], v[154:157], v[114:129]
	v_mfma_f32_32x32x16_f16 v[98:113], v[212:215], v[154:157], v[98:113]
	ds_read_b128 v[240:243], v205 offset:1536
	ds_read_b128 v[244:247], v205 offset:9728
	ds_read_b128 v[208:211], v216 offset:1536
	ds_read_b128 v[212:215], v216 offset:9728
	s_waitcnt lgkmcnt(4)
	v_mfma_f32_32x32x16_f16 v[114:129], v[248:251], v[138:141], v[114:129]
	v_mfma_f32_32x32x16_f16 v[98:113], v[218:221], v[138:141], v[98:113]
	v_mfma_f32_32x32x16_f16 v[114:129], v[196:199], v[146:149], v[114:129]
	v_mfma_f32_32x32x16_f16 v[98:113], v[200:203], v[146:149], v[98:113]
	s_waitcnt lgkmcnt(0)
	v_mfma_f32_32x32x16_f16 v[114:129], v[240:243], v[130:133], v[114:129]
	v_mfma_f32_32x32x16_f16 v[98:113], v[244:247], v[130:133], v[98:113]
	v_mfma_f32_32x32x16_f16 v[114:129], v[208:211], v[134:137], v[114:129]
	v_mfma_f32_32x32x16_f16 v[98:113], v[212:215], v[134:137], v[98:113]
	v_sub_f32_e32 v82, v82, v204
	v_exp_f32_e32 v217, v82
	v_sub_f32_e32 v83, v83, v204
	v_exp_f32_e32 v218, v83
	v_sub_f32_e32 v83, v84, v204
	v_exp_f32_e32 v219, v83
	v_sub_f32_e32 v83, v85, v204
	v_exp_f32_e32 v220, v83
	v_sub_f32_e32 v83, v86, v204
	v_add_f32_e32 v82, 0, v217
	v_exp_f32_e32 v221, v83
	v_sub_f32_e32 v83, v87, v204
	v_add_f32_e32 v82, v218, v82
	v_exp_f32_e32 v224, v83
	v_sub_f32_e32 v83, v88, v204
	v_add_f32_e32 v82, v219, v82
	v_exp_f32_e32 v225, v83
	v_sub_f32_e32 v83, v89, v204
	v_add_f32_e32 v82, v220, v82
	v_exp_f32_e32 v226, v83
	v_add_f32_e32 v82, v221, v82
	v_add_f32_e32 v82, v224, v82
	v_add_f32_e32 v82, v225, v82
	v_add_f32_e32 v227, v226, v82
	v_sub_f32_e32 v90, v90, v204
	v_sub_f32_e32 v91, v91, v204
	v_sub_f32_e32 v66, v66, v204
	v_sub_f32_e32 v67, v67, v204
	s_lshl_b32 s0, s22, 15
	s_and_b32 s9, s0, 0x10000
	v_exp_f32_e32 v208, v90
	v_exp_f32_e32 v209, v91
	v_sub_f32_e32 v91, v92, v204
	v_exp_f32_e32 v210, v91
	v_sub_f32_e32 v91, v93, v204
	v_exp_f32_e32 v211, v91
	v_sub_f32_e32 v91, v94, v204
	v_add_f32_e32 v90, v208, v227
	v_exp_f32_e32 v212, v91
	v_sub_f32_e32 v91, v95, v204
	v_add_f32_e32 v90, v209, v90
	v_exp_f32_e32 v213, v91
	v_sub_f32_e32 v91, v96, v204
	v_add_f32_e32 v90, v210, v90
	v_exp_f32_e32 v214, v91
	v_sub_f32_e32 v91, v97, v204
	v_add_f32_e32 v90, v211, v90
	v_exp_f32_e32 v215, v91
	v_add_f32_e32 v90, v212, v90
	v_add_f32_e32 v90, v213, v90
	v_add_f32_e32 v90, v214, v90
	v_add_f32_e32 v227, v215, v90
	v_add_u32_e32 v205, s9, v192
	v_exp_f32_e32 v196, v66
	v_exp_f32_e32 v197, v67
	v_sub_f32_e32 v67, v68, v204
	v_exp_f32_e32 v198, v67
	v_sub_f32_e32 v67, v69, v204
	v_exp_f32_e32 v199, v67
	v_sub_f32_e32 v67, v70, v204
	v_add_f32_e32 v66, v196, v227
	v_exp_f32_e32 v200, v67
	v_sub_f32_e32 v67, v71, v204
	v_add_f32_e32 v66, v197, v66
	v_exp_f32_e32 v201, v67
	v_sub_f32_e32 v67, v72, v204
	v_add_f32_e32 v66, v198, v66
	v_exp_f32_e32 v202, v67
	v_sub_f32_e32 v67, v73, v204
	v_add_f32_e32 v66, v199, v66
	v_exp_f32_e32 v203, v67
	v_sub_f32_e32 v67, v74, v204
	v_add_f32_e32 v66, v200, v66
	v_add_f32_e32 v66, v201, v66
	v_exp_f32_e32 v86, v67
	v_sub_f32_e32 v67, v75, v204
	v_exp_f32_e32 v87, v67
	v_sub_f32_e32 v67, v76, v204
	v_add_f32_e32 v66, v202, v66
	v_exp_f32_e32 v88, v67
	v_sub_f32_e32 v67, v77, v204
	v_add_f32_e32 v66, v203, v66
	v_exp_f32_e32 v89, v67
	v_sub_f32_e32 v67, v78, v204
	v_add_f32_e32 v66, v86, v66
	v_exp_f32_e32 v90, v67
	v_sub_f32_e32 v67, v79, v204
	v_add_f32_e32 v66, v87, v66
	v_exp_f32_e32 v91, v67
	v_sub_f32_e32 v67, v80, v204
	v_add_f32_e32 v66, v88, v66
	v_exp_f32_e32 v92, v67
	v_sub_f32_e32 v67, v81, v204
	v_add_f32_e32 v66, v89, v66
	v_exp_f32_e32 v93, v67
	v_add_f32_e32 v66, v90, v66
	v_add_f32_e32 v66, v91, v66
	v_add_f32_e32 v66, v92, v66
	v_add_f32_e32 v66, v93, v66
	v_add_f32_e32 v195, v195, v66
	v_add_u32_e32 v204, s9, v1
	ds_read_b64_tr_b16 v[66:67], v204 offset:0
	ds_read_b64_tr_b16 v[68:69], v205 offset:0x800
	ds_read_b64_tr_b16 v[70:71], v204 offset:0x1000
	ds_read_b64_tr_b16 v[72:73], v205 offset:0x1800
	ds_read_b64_tr_b16 v[74:75], v204 offset:0x2000
	ds_read_b64_tr_b16 v[76:77], v205 offset:0x2800
	ds_read_b64_tr_b16 v[78:79], v204 offset:0x3000
	ds_read_b64_tr_b16 v[80:81], v205 offset:0x3800
	s_branch .Lnsa_j1

; #define MFMA(a, b, c) __builtin_amdgcn_mfma_f32_32x32x16_f16((a), (b), (c), 0, 0, 0)
; #define QK_LD(dst, s0) do { dst[0] = *(const f16x8*)(Kst + kbe + 512 * ((s0) >> 1)); dst[1] = *(const f16x8*)(Kst + kbe + 512 * ((s0) >> 1) + 8192); \
;     dst[2] = *(const f16x8*)(Kst + kbo + 512 * ((s0) >> 1)); dst[3] = *(const f16x8*)(Kst + kbo + 512 * ((s0) >> 1) + 8192); } while (0)
; #define QK_LD(dst, s0) do { dst[0] = *(const f16x8*)(Kst + kbe + 512 * ((s0) >> 1)); dst[1] = *(const f16x8*)(Kst + kbe + 512 * ((s0) >> 1) + 8192); \
;     dst[2] = *(const f16x8*)(Kst + kbo + 512 * ((s0) >> 1)); dst[3] = *(const f16x8*)(Kst + kbo + 512 * ((s0) >> 1) + 8192); } while (0)
; #define EXP8(c, b0) do { _Pragma("unroll") for (int j_ = 0; j_ < 8; ++j_) { c[(b0) + j_] = fexp2(c[(b0) + j_] - me); s_ += c[(b0) + j_]; } } while (0)
; DI void qk_exp(f32x16& n0, f32x16& n1, const char* Kst, const f16x8 (&qf)[8], unsigned kbe, unsigned kbo, f32x16& c0, f32x16& c1, float me, float& ps) {
;   const f32x16 zero = {0.f, 0.f, 0.f, 0.f, 0.f, 0.f, 0.f, 0.f, 0.f, 0.f, 0.f, 0.f, 0.f, 0.f, 0.f, 0.f};
;   f16x8 ka[4], kb[4];
;     ...
;   float s_ = 0.f;
;   QK_LD(ka, 0);
;   n0 = MFMA(ka[0], qf[0], zero); n1 = MFMA(ka[1], qf[0], zero); n0 = MFMA(ka[2], qf[1], n0); n1 = MFMA(ka[3], qf[1], n1);
;   QK_LD(kb, 2);
;   EXP8(c0, 0);
;   n0 = MFMA(kb[0], qf[2], n0); n1 = MFMA(kb[1], qf[2], n1); n0 = MFMA(kb[2], qf[3], n0); n1 = MFMA(kb[3], qf[3], n1);
;   QK_LD(ka, 4);
;   EXP8(c0, 8);
;   n0 = MFMA(ka[0], qf[4], n0); n1 = MFMA(ka[1], qf[4], n1); n0 = MFMA(ka[2], qf[5], n0); n1 = MFMA(ka[3], qf[5], n1);
;   QK_LD(kb, 6);
;   EXP8(c1, 0);
;   n0 = MFMA(kb[0], qf[6], n0); n1 = MFMA(kb[1], qf[6], n1); n0 = MFMA(kb[2], qf[7], n0); n1 = MFMA(kb[3], qf[7], n1);
;   EXP8(c1, 8);
;   ps = s_;
;     ...
; }
.LBB0_612:
	v_cndmask_b32_e64 v204, v233, v194, s[0:1]
	s_lshl_b32 s0, s25, 15
	s_and_b32 s7, s0, 0x18000
	s_cmp_lg_u32 s101, 0
	s_cbranch_scc1 .Lnsa_b1
	s_waitcnt lgkmcnt(0)
	v_mfma_f32_32x32x16_f16 v[114:129], v[98:101], v[150:153], 0
	v_sub_f32_e32 v82, v82, v204
	v_exp_f32_e32 v217, v82
	v_sub_f32_e32 v83, v83, v204
	v_exp_f32_e32 v218, v83
	v_sub_f32_e32 v83, v84, v204
	v_exp_f32_e32 v219, v83
	v_sub_f32_e32 v83, v85, v204
	v_mfma_f32_32x32x16_f16 v[98:113], v[102:105], v[150:153], 0
	v_exp_f32_e32 v220, v83
	v_sub_f32_e32 v83, v86, v204
	v_add_f32_e32 v82, 0, v217
	v_exp_f32_e32 v221, v83
	v_sub_f32_e32 v83, v87, v204
	v_add_f32_e32 v82, v218, v82
	v_exp_f32_e32 v224, v83
	v_mfma_f32_32x32x16_f16 v[114:129], v[196:199], v[158:161], v[114:129]
	v_sub_f32_e32 v83, v88, v204
	v_add_f32_e32 v82, v219, v82
	v_exp_f32_e32 v225, v83
	v_sub_f32_e32 v83, v89, v204
	v_add_f32_e32 v82, v220, v82
	v_exp_f32_e32 v226, v83
	v_add_f32_e32 v82, v221, v82
	v_mfma_f32_32x32x16_f16 v[98:113], v[200:203], v[158:161], v[98:113]
	ds_read_b128 v[196:199], v205 offset:512
	ds_read_b128 v[200:203], v205 offset:8704
	ds_read_b128 v[208:211], v216 offset:512
	ds_read_b128 v[212:215], v216 offset:8704
	v_add_f32_e32 v82, v224, v82
	v_add_f32_e32 v82, v225, v82
	v_add_f32_e32 v227, v226, v82
	v_sub_f32_e32 v90, v90, v204
	v_sub_f32_e32 v91, v91, v204
	v_sub_f32_e32 v66, v66, v204
	s_waitcnt lgkmcnt(0)
	v_mfma_f32_32x32x16_f16 v[114:129], v[196:199], v[142:145], v[114:129]
	v_sub_f32_e32 v67, v67, v204
	s_lshl_b32 s0, s22, 15
	s_and_b32 s9, s0, 0x10000
	v_mfma_f32_32x32x16_f16 v[98:113], v[200:203], v[142:145], v[98:113]
	ds_read_b128 v[82:85], v205 offset:1024
	ds_read_b128 v[86:89], v205 offset:9216
	ds_read_b128 v[196:199], v216 offset:1024
	ds_read_b128 v[200:203], v216 offset:9216
	v_mfma_f32_32x32x16_f16 v[114:129], v[208:211], v[154:157], v[114:129]
	v_exp_f32_e32 v208, v90
	v_exp_f32_e32 v209, v91
	v_sub_f32_e32 v91, v92, v204
	v_exp_f32_e32 v210, v91
	v_sub_f32_e32 v91, v93, v204
	v_exp_f32_e32 v211, v91
	v_sub_f32_e32 v91, v94, v204
	v_mfma_f32_32x32x16_f16 v[98:113], v[212:215], v[154:157], v[98:113]
	v_add_f32_e32 v90, v208, v227
	v_exp_f32_e32 v212, v91
	v_sub_f32_e32 v91, v95, v204
	v_add_f32_e32 v90, v209, v90
	v_exp_f32_e32 v213, v91
	v_sub_f32_e32 v91, v96, v204
	v_add_f32_e32 v90, v210, v90
	s_waitcnt lgkmcnt(0)
	v_mfma_f32_32x32x16_f16 v[114:129], v[82:85], v[138:141], v[114:129]
	v_exp_f32_e32 v214, v91
	v_sub_f32_e32 v91, v97, v204
	v_add_f32_e32 v90, v211, v90
	v_exp_f32_e32 v215, v91
	v_add_f32_e32 v90, v212, v90
	v_add_f32_e32 v90, v213, v90
	v_add_f32_e32 v90, v214, v90
	v_mfma_f32_32x32x16_f16 v[98:113], v[86:89], v[138:141], v[98:113]
	v_add_f32_e32 v227, v215, v90
	ds_read_b128 v[82:85], v205 offset:1536
	ds_read_b128 v[86:89], v205 offset:9728
	ds_read_b128 v[90:93], v216 offset:1536
	ds_read_b128 v[94:97], v216 offset:9728
	v_add_u32_e32 v205, s9, v192
	v_mfma_f32_32x32x16_f16 v[114:129], v[196:199], v[146:149], v[114:129]
	v_exp_f32_e32 v196, v66
	v_exp_f32_e32 v197, v67
	v_sub_f32_e32 v67, v68, v204
	v_exp_f32_e32 v198, v67
	v_sub_f32_e32 v67, v69, v204
	v_exp_f32_e32 v199, v67
	v_sub_f32_e32 v67, v70, v204
	v_mfma_f32_32x32x16_f16 v[98:113], v[200:203], v[146:149], v[98:113]
	v_add_f32_e32 v66, v196, v227
	v_exp_f32_e32 v200, v67
	v_sub_f32_e32 v67, v71, v204
	v_add_f32_e32 v66, v197, v66
	v_exp_f32_e32 v201, v67
	v_sub_f32_e32 v67, v72, v204
	v_add_f32_e32 v66, v198, v66
	s_waitcnt lgkmcnt(0)
	v_mfma_f32_32x32x16_f16 v[114:129], v[82:85], v[130:133], v[114:129]
	v_exp_f32_e32 v202, v67
	v_sub_f32_e32 v67, v73, v204
	v_add_f32_e32 v66, v199, v66
	v_exp_f32_e32 v203, v67
	v_sub_f32_e32 v67, v74, v204
	v_add_f32_e32 v66, v200, v66
	v_add_f32_e32 v66, v201, v66
	v_mfma_f32_32x32x16_f16 v[98:113], v[86:89], v[130:133], v[98:113]
	v_exp_f32_e32 v86, v67
	v_sub_f32_e32 v67, v75, v204
	v_exp_f32_e32 v87, v67
	v_sub_f32_e32 v67, v76, v204
	v_add_f32_e32 v66, v202, v66
	v_exp_f32_e32 v88, v67
	v_sub_f32_e32 v67, v77, v204
	v_add_f32_e32 v66, v203, v66
	v_exp_f32_e32 v89, v67
	v_sub_f32_e32 v67, v78, v204
	v_mfma_f32_32x32x16_f16 v[114:129], v[90:93], v[134:137], v[114:129]
	v_add_f32_e32 v66, v86, v66
	v_exp_f32_e32 v90, v67
	v_sub_f32_e32 v67, v79, v204
	v_add_f32_e32 v66, v87, v66
	v_exp_f32_e32 v91, v67
	v_sub_f32_e32 v67, v80, v204
	v_add_f32_e32 v66, v88, v66
	v_exp_f32_e32 v92, v67
	v_sub_f32_e32 v67, v81, v204
	v_add_f32_e32 v66, v89, v66
	v_exp_f32_e32 v93, v67
	v_add_f32_e32 v66, v90, v66
	v_add_f32_e32 v66, v91, v66
	v_add_f32_e32 v66, v92, v66
	v_add_f32_e32 v66, v93, v66
	v_add_f32_e32 v195, v195, v66
	v_add_u32_e32 v204, s9, v1
	ds_read_b64_tr_b16 v[66:67], v204 offset:0
	ds_read_b64_tr_b16 v[68:69], v205 offset:0x800
	ds_read_b64_tr_b16 v[70:71], v204 offset:0x1000
	v_mfma_f32_32x32x16_f16 v[98:113], v[94:97], v[134:137], v[98:113]
	ds_read_b64_tr_b16 v[72:73], v205 offset:0x1800
	ds_read_b64_tr_b16 v[74:75], v204 offset:0x2000
	ds_read_b64_tr_b16 v[76:77], v205 offset:0x2800
	ds_read_b64_tr_b16 v[78:79], v204 offset:0x3000
	ds_read_b64_tr_b16 v[80:81], v205 offset:0x3800
; #define SBAR() __builtin_amdgcn_sched_barrier(0)
; DI void pv_max(f32x16 (&o)[4], unsigned vb0, unsigned vb1, const f32x16& p0, const f32x16& p1, const f32x16& n0, const f32x16& n1, float& pm) {
;   f16x8 pb[4]; pb[0] = pack8(p0, 0); pb[1] = pack8(p0, 1); pb[2] = pack8(p1, 0); pb[3] = pack8(p1, 1);
;   VFrag fa;
;   float mx = n0[0];
;   pv_rd<0>(fa, vb0, vb1);
;   asm volatile("s_waitcnt lgkmcnt(0)" ::: "memory"); SBAR();
;   pv_mm(o[0], fa, pb);
;   pv_rd<1>(fa, vb0, vb1);
; #pragma unroll
;   for (int r = 1; r < 8; ++r) mx = fmaxf(mx, n0[r]);
;   asm volatile("s_waitcnt lgkmcnt(0)" ::: "memory"); SBAR();
;   pv_mm(o[1], fa, pb);
;   pv_rd<2>(fa, vb0, vb1);
; #pragma unroll
;   for (int r = 8; r < 16; ++r) mx = fmaxf(mx, n0[r]);
;   asm volatile("s_waitcnt lgkmcnt(0)" ::: "memory"); SBAR();
;   pv_mm(o[2], fa, pb);
;   pv_rd<3>(fa, vb0, vb1);
; #pragma unroll
;   for (int r = 0; r < 8; ++r) mx = fmaxf(mx, n1[r]);
;   asm volatile("s_waitcnt lgkmcnt(0)" ::: "memory"); SBAR();
;   pv_mm(o[3], fa, pb);
; #pragma unroll
;   for (int r = 8; r < 16; ++r) mx = fmaxf(mx, n1[r]);
;   pm = mx;
; }
.Lnsa_j1:
	s_waitcnt lgkmcnt(0)
	v_cvt_pk_f16_f32 v85, v225, v226
	v_cvt_pk_f16_f32 v84, v221, v224
	v_cvt_pk_f16_f32 v83, v219, v220
	v_cvt_pk_f16_f32 v82, v217, v218
	s_nop 1
	v_mfma_f32_32x32x16_f16 v[50:65], v[66:69], v[82:85], v[50:65]
	v_cvt_pk_f16_f32 v69, v214, v215
	v_cvt_pk_f16_f32 v68, v212, v213
	v_cvt_pk_f16_f32 v67, v210, v211
	v_cvt_pk_f16_f32 v66, v208, v209
	s_nop 1
	v_mfma_f32_32x32x16_f16 v[50:65], v[70:73], v[66:69], v[50:65]
	v_cvt_pk_f16_f32 v73, v202, v203
	v_cvt_pk_f16_f32 v72, v200, v201
	v_cvt_pk_f16_f32 v71, v198, v199
	v_cvt_pk_f16_f32 v70, v196, v197
	v_max_f32_e32 v196, v115, v115
	v_max_f32_e32 v197, v114, v114
	v_max_f32_e32 v196, v197, v196
	v_mfma_f32_32x32x16_f16 v[50:65], v[74:77], v[70:73], v[50:65]
	v_cvt_pk_f16_f32 v77, v92, v93
	v_cvt_pk_f16_f32 v76, v90, v91
	v_cvt_pk_f16_f32 v75, v88, v89
	v_cvt_pk_f16_f32 v74, v86, v87
	v_max3_f32 v196, v196, v116, v117
	v_max3_f32 v196, v196, v118, v119
	v_max3_f32 v196, v196, v120, v121
	v_mfma_f32_32x32x16_f16 v[50:65], v[78:81], v[74:77], v[50:65]
	ds_read_b64_tr_b16 v[78:79], v204 offset:0x200
	ds_read_b64_tr_b16 v[80:81], v205 offset:0xa00
	ds_read_b64_tr_b16 v[86:87], v204 offset:0x1200
	ds_read_b64_tr_b16 v[88:89], v205 offset:0x1a00
	ds_read_b64_tr_b16 v[90:91], v204 offset:0x2200
	ds_read_b64_tr_b16 v[92:93], v205 offset:0x2a00
	ds_read_b64_tr_b16 v[94:95], v204 offset:0x3200
	ds_read_b64_tr_b16 v[96:97], v205 offset:0x3a00
	s_waitcnt lgkmcnt(0)
	s_nop 0
	v_mfma_f32_32x32x16_f16 v[34:49], v[78:81], v[82:85], v[34:49]
	ds_read_b64_tr_b16 v[78:79], v204 offset:0x400
	ds_read_b64_tr_b16 v[80:81], v205 offset:0xc00
	v_max3_f32 v196, v196, v122, v123
	v_max3_f32 v196, v196, v124, v125
	v_max3_f32 v196, v196, v126, v127
	v_max3_f32 v196, v196, v128, v129
	v_mfma_f32_32x32x16_f16 v[34:49], v[86:89], v[66:69], v[34:49]
	ds_read_b64_tr_b16 v[86:87], v204 offset:0x1400
	ds_read_b64_tr_b16 v[88:89], v205 offset:0x1c00
	v_mfma_f32_32x32x16_f16 v[34:49], v[90:93], v[70:73], v[34:49]
	ds_read_b64_tr_b16 v[90:91], v204 offset:0x2400
	ds_read_b64_tr_b16 v[92:93], v205 offset:0x2c00
	v_mfma_f32_32x32x16_f16 v[34:49], v[94:97], v[74:77], v[34:49]
	ds_read_b64_tr_b16 v[94:95], v204 offset:0x3400
	ds_read_b64_tr_b16 v[96:97], v205 offset:0x3c00
	s_waitcnt lgkmcnt(0)
	v_mfma_f32_32x32x16_f16 v[18:33], v[78:81], v[82:85], v[18:33]
	ds_read_b64_tr_b16 v[78:79], v204 offset:0x600
	ds_read_b64_tr_b16 v[80:81], v205 offset:0xe00
	v_max3_f32 v196, v196, v98, v99
	v_max3_f32 v196, v196, v100, v101
	v_max3_f32 v196, v196, v102, v103
	v_max3_f32 v196, v196, v104, v105
	v_mfma_f32_32x32x16_f16 v[18:33], v[86:89], v[66:69], v[18:33]
	ds_read_b64_tr_b16 v[86:87], v204 offset:0x1600
	ds_read_b64_tr_b16 v[88:89], v205 offset:0x1e00
	v_mfma_f32_32x32x16_f16 v[18:33], v[90:93], v[70:73], v[18:33]
	ds_read_b64_tr_b16 v[90:91], v204 offset:0x2600
	ds_read_b64_tr_b16 v[92:93], v205 offset:0x2e00
	v_mfma_f32_32x32x16_f16 v[18:33], v[94:97], v[74:77], v[18:33]
	ds_read_b64_tr_b16 v[94:95], v204 offset:0x3600
	ds_read_b64_tr_b16 v[96:97], v205 offset:0x3e00
	s_waitcnt lgkmcnt(0)
	v_mfma_f32_32x32x16_f16 v[2:17], v[78:81], v[82:85], v[2:17]
	v_max3_f32 v78, v196, v106, v107
	v_max3_f32 v78, v78, v108, v109
	s_add_i32 s0, s24, s16
	v_mfma_f32_32x32x16_f16 v[2:17], v[86:89], v[66:69], v[2:17]
	v_max3_f32 v66, v78, v110, v111
	v_max3_f32 v66, v66, v112, v113
	v_mov_b32_e32 v68, v66
	s_nop 1
	v_permlane32_swap_b32_e32 v66, v68
	v_bfe_u32 v67, v193, s0, 1
	v_max_f32_e32 v68, v68, v68
	v_mfma_f32_32x32x16_f16 v[2:17], v[90:93], v[70:73], v[2:17]
	v_max_f32_e32 v66, v66, v66
	v_max_f32_e32 v66, v66, v68
	v_cmp_eq_u32_e64 s[0:1], 0, v67
	s_nop 1
	v_cndmask_b32_e64 v66, v66, v232, s[0:1]
	v_sub_f32_e32 v67, v66, v194
	v_mfma_f32_32x32x16_f16 v[2:17], v[94:97], v[74:77], v[2:17]
	v_cmp_ge_f32_e32 vcc, s73, v67
	s_cmp_eq_u64 vcc, exec
	s_cbranch_scc1 .LBB0_614
	v_max_f32_e32 v66, v66, v66
	v_max_f32_e32 v67, v194, v194
	v_max_f32_e32 v67, v67, v66
	v_sub_f32_e32 v66, v194, v67
	v_exp_f32_e32 v66, v66
	v_mov_b32_e32 v194, v67
	v_mul_f32_e32 v195, v195, v66
	v_pk_mul_f32 v[64:65], v[64:65], v[66:67] op_sel_hi:[1,0]
	v_pk_mul_f32 v[62:63], v[62:63], v[66:67] op_sel_hi:[1,0]
	v_pk_mul_f32 v[60:61], v[60:61], v[66:67] op_sel_hi:[1,0]
	v_pk_mul_f32 v[58:59], v[58:59], v[66:67] op_sel_hi:[1,0]
	v_pk_mul_f32 v[56:57], v[56:57], v[66:67] op_sel_hi:[1,0]
	v_pk_mul_f32 v[54:55], v[54:55], v[66:67] op_sel_hi:[1,0]
	v_pk_mul_f32 v[52:53], v[52:53], v[66:67] op_sel_hi:[1,0]
	v_pk_mul_f32 v[50:51], v[50:51], v[66:67] op_sel_hi:[1,0]
	v_pk_mul_f32 v[48:49], v[48:49], v[66:67] op_sel_hi:[1,0]
	v_pk_mul_f32 v[46:47], v[46:47], v[66:67] op_sel_hi:[1,0]
	v_pk_mul_f32 v[44:45], v[44:45], v[66:67] op_sel_hi:[1,0]
	v_pk_mul_f32 v[42:43], v[42:43], v[66:67] op_sel_hi:[1,0]
	v_pk_mul_f32 v[40:41], v[40:41], v[66:67] op_sel_hi:[1,0]
	v_pk_mul_f32 v[38:39], v[38:39], v[66:67] op_sel_hi:[1,0]
	v_pk_mul_f32 v[36:37], v[36:37], v[66:67] op_sel_hi:[1,0]
	v_pk_mul_f32 v[34:35], v[34:35], v[66:67] op_sel_hi:[1,0]
	v_pk_mul_f32 v[32:33], v[32:33], v[66:67] op_sel_hi:[1,0]
	v_pk_mul_f32 v[30:31], v[30:31], v[66:67] op_sel_hi:[1,0]
	v_pk_mul_f32 v[28:29], v[28:29], v[66:67] op_sel_hi:[1,0]
	v_pk_mul_f32 v[26:27], v[26:27], v[66:67] op_sel_hi:[1,0]
	v_pk_mul_f32 v[24:25], v[24:25], v[66:67] op_sel_hi:[1,0]
	v_pk_mul_f32 v[22:23], v[22:23], v[66:67] op_sel_hi:[1,0]
	v_pk_mul_f32 v[20:21], v[20:21], v[66:67] op_sel_hi:[1,0]
	v_pk_mul_f32 v[18:19], v[18:19], v[66:67] op_sel_hi:[1,0]
	v_pk_mul_f32 v[16:17], v[16:17], v[66:67] op_sel_hi:[1,0]
	v_pk_mul_f32 v[14:15], v[14:15], v[66:67] op_sel_hi:[1,0]
	v_pk_mul_f32 v[12:13], v[12:13], v[66:67] op_sel_hi:[1,0]
	v_pk_mul_f32 v[10:11], v[10:11], v[66:67] op_sel_hi:[1,0]
	v_pk_mul_f32 v[8:9], v[8:9], v[66:67] op_sel_hi:[1,0]
	v_pk_mul_f32 v[6:7], v[6:7], v[66:67] op_sel_hi:[1,0]
	v_pk_mul_f32 v[4:5], v[4:5], v[66:67] op_sel_hi:[1,0]
	v_pk_mul_f32 v[2:3], v[2:3], v[66:67] op_sel_hi:[1,0]

; #define MFMA(a, b, c) __builtin_amdgcn_mfma_f32_32x32x16_f16((a), (b), (c), 0, 0, 0)
; #define QK_LD(dst, s0) do { dst[0] = *(const f16x8*)(Kst + kbe + 512 * ((s0) >> 1)); dst[1] = *(const f16x8*)(Kst + kbe + 512 * ((s0) >> 1) + 8192); \
;     dst[2] = *(const f16x8*)(Kst + kbo + 512 * ((s0) >> 1)); dst[3] = *(const f16x8*)(Kst + kbo + 512 * ((s0) >> 1) + 8192); } while (0)
; #define QK_LD(dst, s0) do { dst[0] = *(const f16x8*)(Kst + kbe + 512 * ((s0) >> 1)); dst[1] = *(const f16x8*)(Kst + kbe + 512 * ((s0) >> 1) + 8192); \
;     dst[2] = *(const f16x8*)(Kst + kbo + 512 * ((s0) >> 1)); dst[3] = *(const f16x8*)(Kst + kbo + 512 * ((s0) >> 1) + 8192); } while (0)
; #define EXP8(c, b0) do { _Pragma("unroll") for (int j_ = 0; j_ < 8; ++j_) { c[(b0) + j_] = fexp2(c[(b0) + j_] - me); s_ += c[(b0) + j_]; } } while (0)
; DI void qk_exp(f32x16& n0, f32x16& n1, const char* Kst, const f16x8 (&qf)[8], unsigned kbe, unsigned kbo, f32x16& c0, f32x16& c1, float me, float& ps) {
;   const f32x16 zero = {0.f, 0.f, 0.f, 0.f, 0.f, 0.f, 0.f, 0.f, 0.f, 0.f, 0.f, 0.f, 0.f, 0.f, 0.f, 0.f};
;   f16x8 ka[4], kb[4];
;     ...
;   float s_ = 0.f;
;   QK_LD(ka, 0);
;   n0 = MFMA(ka[0], qf[0], zero); n1 = MFMA(ka[1], qf[0], zero); n0 = MFMA(ka[2], qf[1], n0); n1 = MFMA(ka[3], qf[1], n1);
;   QK_LD(kb, 2);
;   EXP8(c0, 0);
;   n0 = MFMA(kb[0], qf[2], n0); n1 = MFMA(kb[1], qf[2], n1); n0 = MFMA(kb[2], qf[3], n0); n1 = MFMA(kb[3], qf[3], n1);
;   QK_LD(ka, 4);
;   EXP8(c0, 8);
;   n0 = MFMA(ka[0], qf[4], n0); n1 = MFMA(ka[1], qf[4], n1); n0 = MFMA(ka[2], qf[5], n0); n1 = MFMA(ka[3], qf[5], n1);
;   QK_LD(kb, 6);
;   EXP8(c1, 0);
;   n0 = MFMA(kb[0], qf[6], n0); n1 = MFMA(kb[1], qf[6], n1); n0 = MFMA(kb[2], qf[7], n0); n1 = MFMA(kb[3], qf[7], n1);
;   EXP8(c1, 8);
;   ps = s_;
;     ...
; }
.Lnsa_b2:
	ds_read_b128 v[240:243], v205 offset:512
	ds_read_b128 v[244:247], v205 offset:8704
	ds_read_b128 v[208:211], v216 offset:512
	ds_read_b128 v[212:215], v216 offset:8704
	s_waitcnt lgkmcnt(4)
	v_mfma_f32_32x32x16_f16 v[82:97], v[66:69], v[150:153], 0
	v_mfma_f32_32x32x16_f16 v[66:81], v[70:73], v[150:153], 0
	v_mfma_f32_32x32x16_f16 v[82:97], v[196:199], v[158:161], v[82:97]
	v_mfma_f32_32x32x16_f16 v[66:81], v[200:203], v[158:161], v[66:81]
	ds_read_b128 v[248:251], v205 offset:1024
	ds_read_b128 v[218:221], v205 offset:9216
	ds_read_b128 v[196:199], v216 offset:1024
	ds_read_b128 v[200:203], v216 offset:9216
	s_waitcnt lgkmcnt(4)
	v_mfma_f32_32x32x16_f16 v[82:97], v[240:243], v[142:145], v[82:97]
	v_mfma_f32_32x32x16_f16 v[66:81], v[244:247], v[142:145], v[66:81]
	v_mfma_f32_32x32x16_f16 v[82:97], v[208:211], v[154:157], v[82:97]
	v_mfma_f32_32x32x16_f16 v[66:81], v[212:215], v[154:157], v[66:81]
	ds_read_b128 v[240:243], v205 offset:1536
	ds_read_b128 v[244:247], v205 offset:9728
	ds_read_b128 v[208:211], v216 offset:1536
	ds_read_b128 v[212:215], v216 offset:9728
	s_waitcnt lgkmcnt(4)
	v_mfma_f32_32x32x16_f16 v[82:97], v[248:251], v[138:141], v[82:97]
	v_mfma_f32_32x32x16_f16 v[66:81], v[218:221], v[138:141], v[66:81]
	v_mfma_f32_32x32x16_f16 v[82:97], v[196:199], v[146:149], v[82:97]
	v_mfma_f32_32x32x16_f16 v[66:81], v[200:203], v[146:149], v[66:81]
	s_waitcnt lgkmcnt(0)
	v_mfma_f32_32x32x16_f16 v[82:97], v[240:243], v[130:133], v[82:97]
	v_mfma_f32_32x32x16_f16 v[66:81], v[244:247], v[130:133], v[66:81]
	v_mfma_f32_32x32x16_f16 v[82:97], v[208:211], v[134:137], v[82:97]
	v_mfma_f32_32x32x16_f16 v[66:81], v[212:215], v[134:137], v[66:81]
	v_sub_f32_e32 v114, v114, v204
	v_exp_f32_e32 v217, v114
	v_sub_f32_e32 v115, v115, v204
	v_exp_f32_e32 v218, v115
	v_sub_f32_e32 v115, v116, v204
	v_exp_f32_e32 v219, v115
	v_sub_f32_e32 v115, v117, v204
	v_exp_f32_e32 v220, v115
	v_sub_f32_e32 v115, v118, v204
	v_add_f32_e32 v114, 0, v217
	v_exp_f32_e32 v221, v115
	v_sub_f32_e32 v115, v119, v204
	v_add_f32_e32 v114, v218, v114
	v_exp_f32_e32 v224, v115
	v_sub_f32_e32 v115, v120, v204
	v_add_f32_e32 v114, v219, v114
	v_exp_f32_e32 v225, v115
	v_sub_f32_e32 v115, v121, v204
	v_add_f32_e32 v114, v220, v114
	v_exp_f32_e32 v226, v115
	v_add_f32_e32 v114, v221, v114
	v_add_f32_e32 v114, v224, v114
	v_add_f32_e32 v114, v225, v114
	v_add_f32_e32 v227, v226, v114
	v_sub_f32_e32 v122, v122, v204
	v_sub_f32_e32 v123, v123, v204
	v_sub_f32_e32 v98, v98, v204
	v_sub_f32_e32 v99, v99, v204
	v_exp_f32_e32 v208, v122
	v_exp_f32_e32 v209, v123
	v_sub_f32_e32 v123, v124, v204
	v_exp_f32_e32 v210, v123
	v_sub_f32_e32 v123, v125, v204
	v_exp_f32_e32 v211, v123
	v_sub_f32_e32 v123, v126, v204
	v_add_f32_e32 v122, v208, v227
	v_exp_f32_e32 v212, v123
	v_sub_f32_e32 v123, v127, v204
	v_add_f32_e32 v122, v209, v122
	v_exp_f32_e32 v213, v123
	v_sub_f32_e32 v123, v128, v204
	v_add_f32_e32 v122, v210, v122
	v_exp_f32_e32 v214, v123
	v_sub_f32_e32 v123, v129, v204
	v_add_f32_e32 v122, v211, v122
	v_exp_f32_e32 v215, v123
	v_add_f32_e32 v122, v212, v122
	v_add_f32_e32 v122, v213, v122
	v_add_f32_e32 v122, v214, v122
	v_add_f32_e32 v227, v215, v122
	v_add_u32_e32 v205, s7, v192
	v_exp_f32_e32 v196, v98
	v_exp_f32_e32 v197, v99
	v_sub_f32_e32 v99, v100, v204
	v_exp_f32_e32 v198, v99
	v_sub_f32_e32 v99, v101, v204
	v_exp_f32_e32 v199, v99
	v_sub_f32_e32 v99, v102, v204
	v_add_f32_e32 v98, v196, v227
	v_exp_f32_e32 v200, v99
	v_sub_f32_e32 v99, v103, v204
	v_add_f32_e32 v98, v197, v98
	v_exp_f32_e32 v201, v99
	v_sub_f32_e32 v99, v104, v204
	v_add_f32_e32 v98, v198, v98
	v_exp_f32_e32 v202, v99
	v_sub_f32_e32 v99, v105, v204
	v_add_f32_e32 v98, v199, v98
	v_exp_f32_e32 v203, v99
	v_sub_f32_e32 v99, v106, v204
	v_add_f32_e32 v98, v200, v98
	v_add_f32_e32 v98, v201, v98
	v_exp_f32_e32 v118, v99
	v_sub_f32_e32 v99, v107, v204
	v_exp_f32_e32 v119, v99
	v_sub_f32_e32 v99, v108, v204
	v_add_f32_e32 v98, v202, v98
	v_exp_f32_e32 v120, v99
	v_sub_f32_e32 v99, v109, v204
	v_add_f32_e32 v98, v203, v98
	v_exp_f32_e32 v121, v99
	v_sub_f32_e32 v99, v110, v204
	v_add_f32_e32 v98, v118, v98
	v_exp_f32_e32 v122, v99
	v_sub_f32_e32 v99, v111, v204
	v_add_f32_e32 v98, v119, v98
	v_exp_f32_e32 v123, v99
	v_sub_f32_e32 v99, v112, v204
	v_add_f32_e32 v98, v120, v98
	v_exp_f32_e32 v124, v99
	v_sub_f32_e32 v99, v113, v204
	v_add_f32_e32 v98, v121, v98
	v_exp_f32_e32 v125, v99
	v_add_f32_e32 v98, v122, v98
	v_add_f32_e32 v98, v123, v98
	v_add_f32_e32 v98, v124, v98
	v_add_f32_e32 v98, v125, v98
	v_add_f32_e32 v195, v195, v98
	v_add_u32_e32 v204, s7, v1
	ds_read_b64_tr_b16 v[98:99], v204 offset:0
	ds_read_b64_tr_b16 v[100:101], v205 offset:0x800
	ds_read_b64_tr_b16 v[102:103], v204 offset:0x1000
	ds_read_b64_tr_b16 v[104:105], v205 offset:0x1800
	ds_read_b64_tr_b16 v[106:107], v204 offset:0x2000
	ds_read_b64_tr_b16 v[108:109], v205 offset:0x2800
	ds_read_b64_tr_b16 v[110:111], v204 offset:0x3000
	ds_read_b64_tr_b16 v[112:113], v205 offset:0x3800
	s_branch .Lnsa_j2

; #define MFMA(a, b, c) __builtin_amdgcn_mfma_f32_32x32x16_f16((a), (b), (c), 0, 0, 0)
; #define QK_LD(dst, s0) do { dst[0] = *(const f16x8*)(Kst + kbe + 512 * ((s0) >> 1)); dst[1] = *(const f16x8*)(Kst + kbe + 512 * ((s0) >> 1) + 8192); \
;     dst[2] = *(const f16x8*)(Kst + kbo + 512 * ((s0) >> 1)); dst[3] = *(const f16x8*)(Kst + kbo + 512 * ((s0) >> 1) + 8192); } while (0)
; #define QK_LD(dst, s0) do { dst[0] = *(const f16x8*)(Kst + kbe + 512 * ((s0) >> 1)); dst[1] = *(const f16x8*)(Kst + kbe + 512 * ((s0) >> 1) + 8192); \
;     dst[2] = *(const f16x8*)(Kst + kbo + 512 * ((s0) >> 1)); dst[3] = *(const f16x8*)(Kst + kbo + 512 * ((s0) >> 1) + 8192); } while (0)
; #define EXP8(c, b0) do { _Pragma("unroll") for (int j_ = 0; j_ < 8; ++j_) { c[(b0) + j_] = fexp2(c[(b0) + j_] - me); s_ += c[(b0) + j_]; } } while (0)
; DI void qk_exp(f32x16& n0, f32x16& n1, const char* Kst, const f16x8 (&qf)[8], unsigned kbe, unsigned kbo, f32x16& c0, f32x16& c1, float me, float& ps) {
;   const f32x16 zero = {0.f, 0.f, 0.f, 0.f, 0.f, 0.f, 0.f, 0.f, 0.f, 0.f, 0.f, 0.f, 0.f, 0.f, 0.f, 0.f};
;   f16x8 ka[4], kb[4];
;     ...
;   float s_ = 0.f;
;   QK_LD(ka, 0);
;   n0 = MFMA(ka[0], qf[0], zero); n1 = MFMA(ka[1], qf[0], zero); n0 = MFMA(ka[2], qf[1], n0); n1 = MFMA(ka[3], qf[1], n1);
;   QK_LD(kb, 2);
;   EXP8(c0, 0);
;   n0 = MFMA(kb[0], qf[2], n0); n1 = MFMA(kb[1], qf[2], n1); n0 = MFMA(kb[2], qf[3], n0); n1 = MFMA(kb[3], qf[3], n1);
;   QK_LD(ka, 4);
;   EXP8(c0, 8);
;   n0 = MFMA(ka[0], qf[4], n0); n1 = MFMA(ka[1], qf[4], n1); n0 = MFMA(ka[2], qf[5], n0); n1 = MFMA(ka[3], qf[5], n1);
;   QK_LD(kb, 6);
;   EXP8(c1, 0);
;   n0 = MFMA(kb[0], qf[6], n0); n1 = MFMA(kb[1], qf[6], n1); n0 = MFMA(kb[2], qf[7], n0); n1 = MFMA(kb[3], qf[7], n1);
;   EXP8(c1, 8);
;   ps = s_;
;     ...
; }
.LBB0_637:
	v_cndmask_b32_e64 v204, v194, v233, s[0:1]
	s_cmp_lg_u32 s101, 0
	s_cbranch_scc1 .Lnsa_b2
	s_waitcnt lgkmcnt(0)
	v_mfma_f32_32x32x16_f16 v[82:97], v[66:69], v[150:153], 0
	v_sub_f32_e32 v114, v114, v204
	v_exp_f32_e32 v217, v114
	v_sub_f32_e32 v115, v115, v204
	v_exp_f32_e32 v218, v115
	v_sub_f32_e32 v115, v116, v204
	v_exp_f32_e32 v219, v115
	v_sub_f32_e32 v115, v117, v204
	v_mfma_f32_32x32x16_f16 v[66:81], v[70:73], v[150:153], 0
	v_exp_f32_e32 v220, v115
	v_sub_f32_e32 v115, v118, v204
	v_add_f32_e32 v114, 0, v217
	v_exp_f32_e32 v221, v115
	v_sub_f32_e32 v115, v119, v204
	v_add_f32_e32 v114, v218, v114
	v_exp_f32_e32 v224, v115
	v_mfma_f32_32x32x16_f16 v[82:97], v[196:199], v[158:161], v[82:97]
	v_sub_f32_e32 v115, v120, v204
	v_add_f32_e32 v114, v219, v114
	v_exp_f32_e32 v225, v115
	v_sub_f32_e32 v115, v121, v204
	v_add_f32_e32 v114, v220, v114
	v_exp_f32_e32 v226, v115
	v_add_f32_e32 v114, v221, v114
	v_mfma_f32_32x32x16_f16 v[66:81], v[200:203], v[158:161], v[66:81]
	ds_read_b128 v[196:199], v205 offset:512
	ds_read_b128 v[200:203], v205 offset:8704
	ds_read_b128 v[208:211], v216 offset:512
	ds_read_b128 v[212:215], v216 offset:8704
	v_add_f32_e32 v114, v224, v114
	v_add_f32_e32 v114, v225, v114
	v_add_f32_e32 v227, v226, v114
	v_sub_f32_e32 v122, v122, v204
	v_sub_f32_e32 v123, v123, v204
	v_sub_f32_e32 v98, v98, v204
	s_waitcnt lgkmcnt(0)
	v_mfma_f32_32x32x16_f16 v[82:97], v[196:199], v[142:145], v[82:97]
	v_sub_f32_e32 v99, v99, v204
	v_mfma_f32_32x32x16_f16 v[66:81], v[200:203], v[142:145], v[66:81]
	ds_read_b128 v[114:117], v205 offset:1024
	ds_read_b128 v[118:121], v205 offset:9216
	ds_read_b128 v[196:199], v216 offset:1024
	ds_read_b128 v[200:203], v216 offset:9216
	v_mfma_f32_32x32x16_f16 v[82:97], v[208:211], v[154:157], v[82:97]
	v_exp_f32_e32 v208, v122
	v_exp_f32_e32 v209, v123
	v_sub_f32_e32 v123, v124, v204
	v_exp_f32_e32 v210, v123
	v_sub_f32_e32 v123, v125, v204
	v_exp_f32_e32 v211, v123
	v_sub_f32_e32 v123, v126, v204
	v_mfma_f32_32x32x16_f16 v[66:81], v[212:215], v[154:157], v[66:81]
	v_add_f32_e32 v122, v208, v227
	v_exp_f32_e32 v212, v123
	v_sub_f32_e32 v123, v127, v204
	v_add_f32_e32 v122, v209, v122
	v_exp_f32_e32 v213, v123
	v_sub_f32_e32 v123, v128, v204
	v_add_f32_e32 v122, v210, v122
	s_waitcnt lgkmcnt(0)
	v_mfma_f32_32x32x16_f16 v[82:97], v[114:117], v[138:141], v[82:97]
	v_exp_f32_e32 v214, v123
	v_sub_f32_e32 v123, v129, v204
	v_add_f32_e32 v122, v211, v122
	v_exp_f32_e32 v215, v123
	v_add_f32_e32 v122, v212, v122
	v_add_f32_e32 v122, v213, v122
	v_add_f32_e32 v122, v214, v122
	v_mfma_f32_32x32x16_f16 v[66:81], v[118:121], v[138:141], v[66:81]
	v_add_f32_e32 v227, v215, v122
	ds_read_b128 v[114:117], v205 offset:1536
	ds_read_b128 v[118:121], v205 offset:9728
	ds_read_b128 v[122:125], v216 offset:1536
	ds_read_b128 v[126:129], v216 offset:9728
	v_add_u32_e32 v205, s7, v192
	v_mfma_f32_32x32x16_f16 v[82:97], v[196:199], v[146:149], v[82:97]
	v_exp_f32_e32 v196, v98
	v_exp_f32_e32 v197, v99
	v_sub_f32_e32 v99, v100, v204
	v_exp_f32_e32 v198, v99
	v_sub_f32_e32 v99, v101, v204
	v_exp_f32_e32 v199, v99
	v_sub_f32_e32 v99, v102, v204
	v_mfma_f32_32x32x16_f16 v[66:81], v[200:203], v[146:149], v[66:81]
	v_add_f32_e32 v98, v196, v227
	v_exp_f32_e32 v200, v99
	v_sub_f32_e32 v99, v103, v204
	v_add_f32_e32 v98, v197, v98
	v_exp_f32_e32 v201, v99
	v_sub_f32_e32 v99, v104, v204
	v_add_f32_e32 v98, v198, v98
	s_waitcnt lgkmcnt(0)
	v_mfma_f32_32x32x16_f16 v[82:97], v[114:117], v[130:133], v[82:97]
	v_exp_f32_e32 v202, v99
	v_sub_f32_e32 v99, v105, v204
	v_add_f32_e32 v98, v199, v98
	v_exp_f32_e32 v203, v99
	v_sub_f32_e32 v99, v106, v204
	v_add_f32_e32 v98, v200, v98
	v_add_f32_e32 v98, v201, v98
	v_mfma_f32_32x32x16_f16 v[66:81], v[118:121], v[130:133], v[66:81]
	v_exp_f32_e32 v118, v99
	v_sub_f32_e32 v99, v107, v204
	v_exp_f32_e32 v119, v99
	v_sub_f32_e32 v99, v108, v204
	v_add_f32_e32 v98, v202, v98
	v_exp_f32_e32 v120, v99
	v_sub_f32_e32 v99, v109, v204
	v_add_f32_e32 v98, v203, v98
	v_exp_f32_e32 v121, v99
	v_sub_f32_e32 v99, v110, v204
	v_mfma_f32_32x32x16_f16 v[82:97], v[122:125], v[134:137], v[82:97]
	v_add_f32_e32 v98, v118, v98
	v_exp_f32_e32 v122, v99
	v_sub_f32_e32 v99, v111, v204
	v_add_f32_e32 v98, v119, v98
	v_exp_f32_e32 v123, v99
	v_sub_f32_e32 v99, v112, v204
	v_add_f32_e32 v98, v120, v98
	v_exp_f32_e32 v124, v99
	v_sub_f32_e32 v99, v113, v204
	v_add_f32_e32 v98, v121, v98
	v_exp_f32_e32 v125, v99
	v_add_f32_e32 v98, v122, v98
	v_add_f32_e32 v98, v123, v98
	v_add_f32_e32 v98, v124, v98
	v_add_f32_e32 v98, v125, v98
	v_add_f32_e32 v195, v195, v98
	v_add_u32_e32 v204, s7, v1
	ds_read_b64_tr_b16 v[98:99], v204 offset:0
	ds_read_b64_tr_b16 v[100:101], v205 offset:0x800
	ds_read_b64_tr_b16 v[102:103], v204 offset:0x1000
	v_mfma_f32_32x32x16_f16 v[66:81], v[126:129], v[134:137], v[66:81]
	ds_read_b64_tr_b16 v[104:105], v205 offset:0x1800
	ds_read_b64_tr_b16 v[106:107], v204 offset:0x2000
	ds_read_b64_tr_b16 v[108:109], v205 offset:0x2800
	ds_read_b64_tr_b16 v[110:111], v204 offset:0x3000
	ds_read_b64_tr_b16 v[112:113], v205 offset:0x3800
; #define SBAR() __builtin_amdgcn_sched_barrier(0)
; DI void pv_max(f32x16 (&o)[4], unsigned vb0, unsigned vb1, const f32x16& p0, const f32x16& p1, const f32x16& n0, const f32x16& n1, float& pm) {
;   f16x8 pb[4]; pb[0] = pack8(p0, 0); pb[1] = pack8(p0, 1); pb[2] = pack8(p1, 0); pb[3] = pack8(p1, 1);
;   VFrag fa;
;   float mx = n0[0];
;   pv_rd<0>(fa, vb0, vb1);
;   asm volatile("s_waitcnt lgkmcnt(0)" ::: "memory"); SBAR();
;   pv_mm(o[0], fa, pb);
;   pv_rd<1>(fa, vb0, vb1);
; #pragma unroll
;   for (int r = 1; r < 8; ++r) mx = fmaxf(mx, n0[r]);
;   asm volatile("s_waitcnt lgkmcnt(0)" ::: "memory"); SBAR();
;   pv_mm(o[1], fa, pb);
;   pv_rd<2>(fa, vb0, vb1);
; #pragma unroll
;   for (int r = 8; r < 16; ++r) mx = fmaxf(mx, n0[r]);
;   asm volatile("s_waitcnt lgkmcnt(0)" ::: "memory"); SBAR();
;   pv_mm(o[2], fa, pb);
;   pv_rd<3>(fa, vb0, vb1);
; #pragma unroll
;   for (int r = 0; r < 8; ++r) mx = fmaxf(mx, n1[r]);
;   asm volatile("s_waitcnt lgkmcnt(0)" ::: "memory"); SBAR();
;   pv_mm(o[3], fa, pb);
; #pragma unroll
;   for (int r = 8; r < 16; ++r) mx = fmaxf(mx, n1[r]);
;   pm = mx;
; }
.Lnsa_j2:
	s_waitcnt lgkmcnt(0)
	v_cvt_pk_f16_f32 v117, v225, v226
	v_cvt_pk_f16_f32 v116, v221, v224
	v_cvt_pk_f16_f32 v115, v219, v220
	v_cvt_pk_f16_f32 v114, v217, v218
	s_nop 1
	v_mfma_f32_32x32x16_f16 v[50:65], v[98:101], v[114:117], v[50:65]
	v_cvt_pk_f16_f32 v101, v214, v215
	v_cvt_pk_f16_f32 v100, v212, v213
	v_cvt_pk_f16_f32 v99, v210, v211
	v_cvt_pk_f16_f32 v98, v208, v209
	s_nop 1
	v_mfma_f32_32x32x16_f16 v[50:65], v[102:105], v[98:101], v[50:65]
	v_cvt_pk_f16_f32 v105, v202, v203
	v_cvt_pk_f16_f32 v104, v200, v201
	v_cvt_pk_f16_f32 v103, v198, v199
	v_cvt_pk_f16_f32 v102, v196, v197
	v_max_f32_e32 v196, v83, v83
	v_max_f32_e32 v197, v82, v82
	v_max_f32_e32 v196, v197, v196
	v_mfma_f32_32x32x16_f16 v[50:65], v[106:109], v[102:105], v[50:65]
	v_cvt_pk_f16_f32 v109, v124, v125
	v_cvt_pk_f16_f32 v108, v122, v123
	v_cvt_pk_f16_f32 v107, v120, v121
	v_cvt_pk_f16_f32 v106, v118, v119
	v_max3_f32 v196, v196, v84, v85
	v_max3_f32 v196, v196, v86, v87
	v_max3_f32 v196, v196, v88, v89
	v_mfma_f32_32x32x16_f16 v[50:65], v[110:113], v[106:109], v[50:65]
	ds_read_b64_tr_b16 v[110:111], v204 offset:0x200
	ds_read_b64_tr_b16 v[112:113], v205 offset:0xa00
	ds_read_b64_tr_b16 v[118:119], v204 offset:0x1200
	ds_read_b64_tr_b16 v[120:121], v205 offset:0x1a00
	ds_read_b64_tr_b16 v[122:123], v204 offset:0x2200
	ds_read_b64_tr_b16 v[124:125], v205 offset:0x2a00
	ds_read_b64_tr_b16 v[126:127], v204 offset:0x3200
	ds_read_b64_tr_b16 v[128:129], v205 offset:0x3a00
	s_waitcnt lgkmcnt(0)
	s_nop 0
	v_mfma_f32_32x32x16_f16 v[34:49], v[110:113], v[114:117], v[34:49]
	ds_read_b64_tr_b16 v[110:111], v204 offset:0x400
	ds_read_b64_tr_b16 v[112:113], v205 offset:0xc00
	v_max3_f32 v196, v196, v90, v91
	v_max3_f32 v196, v196, v92, v93
	v_max3_f32 v196, v196, v94, v95
	v_max3_f32 v196, v196, v96, v97
	v_mfma_f32_32x32x16_f16 v[34:49], v[118:121], v[98:101], v[34:49]
	ds_read_b64_tr_b16 v[118:119], v204 offset:0x1400
	ds_read_b64_tr_b16 v[120:121], v205 offset:0x1c00
	v_mfma_f32_32x32x16_f16 v[34:49], v[122:125], v[102:105], v[34:49]
	ds_read_b64_tr_b16 v[122:123], v204 offset:0x2400
	ds_read_b64_tr_b16 v[124:125], v205 offset:0x2c00
	v_mfma_f32_32x32x16_f16 v[34:49], v[126:129], v[106:109], v[34:49]
	ds_read_b64_tr_b16 v[126:127], v204 offset:0x3400
	ds_read_b64_tr_b16 v[128:129], v205 offset:0x3c00
	s_waitcnt lgkmcnt(0)
	v_mfma_f32_32x32x16_f16 v[18:33], v[110:113], v[114:117], v[18:33]
	ds_read_b64_tr_b16 v[110:111], v204 offset:0x600
	ds_read_b64_tr_b16 v[112:113], v205 offset:0xe00
	v_max3_f32 v196, v196, v66, v67
	v_max3_f32 v196, v196, v68, v69
	v_max3_f32 v196, v196, v70, v71
	v_max3_f32 v196, v196, v72, v73
	v_mfma_f32_32x32x16_f16 v[18:33], v[118:121], v[98:101], v[18:33]
	ds_read_b64_tr_b16 v[118:119], v204 offset:0x1600
	ds_read_b64_tr_b16 v[120:121], v205 offset:0x1e00
	v_mfma_f32_32x32x16_f16 v[18:33], v[122:125], v[102:105], v[18:33]
	ds_read_b64_tr_b16 v[122:123], v204 offset:0x2600
	ds_read_b64_tr_b16 v[124:125], v205 offset:0x2e00
	v_mfma_f32_32x32x16_f16 v[18:33], v[126:129], v[106:109], v[18:33]
	ds_read_b64_tr_b16 v[126:127], v204 offset:0x3600
	ds_read_b64_tr_b16 v[128:129], v205 offset:0x3e00
	s_waitcnt lgkmcnt(0)
	v_mfma_f32_32x32x16_f16 v[2:17], v[110:113], v[114:117], v[2:17]
	v_max3_f32 v110, v196, v74, v75
	v_max3_f32 v110, v110, v76, v77
	v_max3_f32 v110, v110, v78, v79
	s_sub_i32 s0, s62, s22
	v_mfma_f32_32x32x16_f16 v[2:17], v[118:121], v[98:101], v[2:17]
	v_max3_f32 v98, v110, v80, v81
	v_mov_b32_e32 v100, v98
	v_lshrrev_b32_e32 v99, s0, v193
	s_nop 0
	v_permlane32_swap_b32_e32 v98, v100
	v_and_b32_e32 v99, 1, v99
	v_max_f32_e32 v100, v100, v100
	v_mfma_f32_32x32x16_f16 v[2:17], v[122:125], v[102:105], v[2:17]
	v_max_f32_e32 v98, v98, v98
	v_max_f32_e32 v98, v98, v100
	v_cmp_eq_u32_e64 s[0:1], 1, v99
	s_nop 1
	v_cndmask_b32_e64 v98, v232, v98, s[0:1]
	v_sub_f32_e32 v99, v98, v194
	v_mfma_f32_32x32x16_f16 v[2:17], v[126:129], v[106:109], v[2:17]
	v_cmp_ge_f32_e32 vcc, s73, v99
	s_cmp_eq_u64 vcc, exec
	s_cbranch_scc1 .LBB0_639
	v_max_f32_e32 v98, v98, v98
	v_max_f32_e32 v99, v194, v194
	v_max_f32_e32 v99, v99, v98
	v_sub_f32_e32 v98, v194, v99
	v_exp_f32_e32 v98, v98
	v_mov_b32_e32 v194, v99
	v_mul_f32_e32 v195, v195, v98
	v_pk_mul_f32 v[64:65], v[64:65], v[98:99] op_sel_hi:[1,0]
	v_pk_mul_f32 v[62:63], v[62:63], v[98:99] op_sel_hi:[1,0]
	v_pk_mul_f32 v[60:61], v[60:61], v[98:99] op_sel_hi:[1,0]
	v_pk_mul_f32 v[58:59], v[58:59], v[98:99] op_sel_hi:[1,0]
	v_pk_mul_f32 v[56:57], v[56:57], v[98:99] op_sel_hi:[1,0]
	v_pk_mul_f32 v[54:55], v[54:55], v[98:99] op_sel_hi:[1,0]
	v_pk_mul_f32 v[52:53], v[52:53], v[98:99] op_sel_hi:[1,0]
	v_pk_mul_f32 v[50:51], v[50:51], v[98:99] op_sel_hi:[1,0]
	v_pk_mul_f32 v[48:49], v[48:49], v[98:99] op_sel_hi:[1,0]
	v_pk_mul_f32 v[46:47], v[46:47], v[98:99] op_sel_hi:[1,0]
	v_pk_mul_f32 v[44:45], v[44:45], v[98:99] op_sel_hi:[1,0]
	v_pk_mul_f32 v[42:43], v[42:43], v[98:99] op_sel_hi:[1,0]
	v_pk_mul_f32 v[40:41], v[40:41], v[98:99] op_sel_hi:[1,0]
	v_pk_mul_f32 v[38:39], v[38:39], v[98:99] op_sel_hi:[1,0]
	v_pk_mul_f32 v[36:37], v[36:37], v[98:99] op_sel_hi:[1,0]
	v_pk_mul_f32 v[34:35], v[34:35], v[98:99] op_sel_hi:[1,0]
	v_pk_mul_f32 v[32:33], v[32:33], v[98:99] op_sel_hi:[1,0]
	v_pk_mul_f32 v[30:31], v[30:31], v[98:99] op_sel_hi:[1,0]
	v_pk_mul_f32 v[28:29], v[28:29], v[98:99] op_sel_hi:[1,0]
	v_pk_mul_f32 v[26:27], v[26:27], v[98:99] op_sel_hi:[1,0]
	v_pk_mul_f32 v[24:25], v[24:25], v[98:99] op_sel_hi:[1,0]
	v_pk_mul_f32 v[22:23], v[22:23], v[98:99] op_sel_hi:[1,0]
	v_pk_mul_f32 v[20:21], v[20:21], v[98:99] op_sel_hi:[1,0]
	v_pk_mul_f32 v[18:19], v[18:19], v[98:99] op_sel_hi:[1,0]
	v_pk_mul_f32 v[16:17], v[16:17], v[98:99] op_sel_hi:[1,0]
	v_pk_mul_f32 v[14:15], v[14:15], v[98:99] op_sel_hi:[1,0]
	v_pk_mul_f32 v[12:13], v[12:13], v[98:99] op_sel_hi:[1,0]
	v_pk_mul_f32 v[10:11], v[10:11], v[98:99] op_sel_hi:[1,0]
	v_pk_mul_f32 v[8:9], v[8:9], v[98:99] op_sel_hi:[1,0]
	v_pk_mul_f32 v[6:7], v[6:7], v[98:99] op_sel_hi:[1,0]
	v_pk_mul_f32 v[4:5], v[4:5], v[98:99] op_sel_hi:[1,0]
	v_pk_mul_f32 v[2:3], v[2:3], v[98:99] op_sel_hi:[1,0]

; #define MFMA(a, b, c) __builtin_amdgcn_mfma_f32_32x32x16_f16((a), (b), (c), 0, 0, 0)
; #define QK_LD(dst, s0) do { dst[0] = *(const f16x8*)(Kst + kbe + 512 * ((s0) >> 1)); dst[1] = *(const f16x8*)(Kst + kbe + 512 * ((s0) >> 1) + 8192); \
;     dst[2] = *(const f16x8*)(Kst + kbo + 512 * ((s0) >> 1)); dst[3] = *(const f16x8*)(Kst + kbo + 512 * ((s0) >> 1) + 8192); } while (0)
; #define QK_LD(dst, s0) do { dst[0] = *(const f16x8*)(Kst + kbe + 512 * ((s0) >> 1)); dst[1] = *(const f16x8*)(Kst + kbe + 512 * ((s0) >> 1) + 8192); \
;     dst[2] = *(const f16x8*)(Kst + kbo + 512 * ((s0) >> 1)); dst[3] = *(const f16x8*)(Kst + kbo + 512 * ((s0) >> 1) + 8192); } while (0)
; #define EXP8(c, b0) do { _Pragma("unroll") for (int j_ = 0; j_ < 8; ++j_) { c[(b0) + j_] = fexp2(c[(b0) + j_] - me); s_ += c[(b0) + j_]; } } while (0)
; DI void qk_exp(f32x16& n0, f32x16& n1, const char* Kst, const f16x8 (&qf)[8], unsigned kbe, unsigned kbo, f32x16& c0, f32x16& c1, float me, float& ps) {
;   const f32x16 zero = {0.f, 0.f, 0.f, 0.f, 0.f, 0.f, 0.f, 0.f, 0.f, 0.f, 0.f, 0.f, 0.f, 0.f, 0.f, 0.f};
;   f16x8 ka[4], kb[4];
;     ...
;   float s_ = 0.f;
;   QK_LD(ka, 0);
;   n0 = MFMA(ka[0], qf[0], zero); n1 = MFMA(ka[1], qf[0], zero); n0 = MFMA(ka[2], qf[1], n0); n1 = MFMA(ka[3], qf[1], n1);
;   QK_LD(kb, 2);
;   EXP8(c0, 0);
;   n0 = MFMA(kb[0], qf[2], n0); n1 = MFMA(kb[1], qf[2], n1); n0 = MFMA(kb[2], qf[3], n0); n1 = MFMA(kb[3], qf[3], n1);
;   QK_LD(ka, 4);
;   EXP8(c0, 8);
;   n0 = MFMA(ka[0], qf[4], n0); n1 = MFMA(ka[1], qf[4], n1); n0 = MFMA(ka[2], qf[5], n0); n1 = MFMA(ka[3], qf[5], n1);
;   QK_LD(kb, 6);
;   EXP8(c1, 0);
;   n0 = MFMA(kb[0], qf[6], n0); n1 = MFMA(kb[1], qf[6], n1); n0 = MFMA(kb[2], qf[7], n0); n1 = MFMA(kb[3], qf[7], n1);
;   EXP8(c1, 8);
;   ps = s_;
;     ...
; }
.Lnsa_b3:
	ds_read_b128 v[240:243], v212 offset:512
	ds_read_b128 v[244:247], v212 offset:8704
	ds_read_b128 v[202:205], v213 offset:512
	ds_read_b128 v[208:211], v213 offset:8704
	s_waitcnt lgkmcnt(4)
	v_mfma_f32_32x32x16_f16 v[114:129], v[98:101], v[150:153], 0
	v_mfma_f32_32x32x16_f16 v[98:113], v[102:105], v[150:153], 0
	v_mfma_f32_32x32x16_f16 v[114:129], v[194:197], v[158:161], v[114:129]
	v_mfma_f32_32x32x16_f16 v[98:113], v[198:201], v[158:161], v[98:113]
	ds_read_b128 v[248:251], v212 offset:1024
	ds_read_b128 v[214:217], v212 offset:9216
	ds_read_b128 v[194:197], v213 offset:1024
	ds_read_b128 v[198:201], v213 offset:9216
	s_waitcnt lgkmcnt(4)
	v_mfma_f32_32x32x16_f16 v[114:129], v[240:243], v[142:145], v[114:129]
	v_mfma_f32_32x32x16_f16 v[98:113], v[244:247], v[142:145], v[98:113]
	v_mfma_f32_32x32x16_f16 v[114:129], v[202:205], v[154:157], v[114:129]
	v_mfma_f32_32x32x16_f16 v[98:113], v[208:211], v[154:157], v[98:113]
	ds_read_b128 v[240:243], v212 offset:1536
	ds_read_b128 v[244:247], v212 offset:9728
	ds_read_b128 v[202:205], v213 offset:1536
	ds_read_b128 v[208:211], v213 offset:9728
	s_waitcnt lgkmcnt(4)
	v_mfma_f32_32x32x16_f16 v[114:129], v[248:251], v[138:141], v[114:129]
	v_mfma_f32_32x32x16_f16 v[98:113], v[214:217], v[138:141], v[98:113]
	v_mfma_f32_32x32x16_f16 v[114:129], v[194:197], v[146:149], v[114:129]
	v_mfma_f32_32x32x16_f16 v[98:113], v[198:201], v[146:149], v[98:113]
	s_waitcnt lgkmcnt(0)
	v_mfma_f32_32x32x16_f16 v[114:129], v[240:243], v[130:133], v[114:129]
	v_mfma_f32_32x32x16_f16 v[98:113], v[244:247], v[130:133], v[98:113]
	v_mfma_f32_32x32x16_f16 v[114:129], v[202:205], v[134:137], v[114:129]
	v_mfma_f32_32x32x16_f16 v[98:113], v[208:211], v[134:137], v[98:113]
	v_exp_f32_e32 v214, v66
	v_sub_f32_e32 v67, v67, v191
	v_exp_f32_e32 v215, v67
	v_sub_f32_e32 v67, v68, v191
	v_exp_f32_e32 v216, v67
	v_sub_f32_e32 v67, v69, v191
	v_exp_f32_e32 v217, v67
	v_sub_f32_e32 v67, v70, v191
	v_add_f32_e32 v66, 0, v214
	v_exp_f32_e32 v218, v67
	v_sub_f32_e32 v67, v71, v191
	v_add_f32_e32 v66, v215, v66
	v_exp_f32_e32 v219, v67
	v_sub_f32_e32 v67, v72, v191
	v_add_f32_e32 v66, v216, v66
	v_exp_f32_e32 v220, v67
	v_sub_f32_e32 v67, v73, v191
	v_add_f32_e32 v66, v217, v66
	v_exp_f32_e32 v221, v67
	v_add_f32_e32 v66, v218, v66
	v_add_f32_e32 v66, v219, v66
	v_add_f32_e32 v66, v220, v66
	v_add_f32_e32 v224, v221, v66
	v_sub_f32_e32 v74, v74, v191
	v_sub_f32_e32 v75, v75, v191
	v_sub_f32_e32 v82, v82, v191
	v_sub_f32_e32 v83, v83, v191
	s_lshl_b32 s0, s5, 15
	s_and_b32 s21, s0, 0x18000
	v_exp_f32_e32 v202, v74
	v_exp_f32_e32 v203, v75
	v_sub_f32_e32 v75, v76, v191
	v_exp_f32_e32 v204, v75
	v_sub_f32_e32 v75, v77, v191
	v_exp_f32_e32 v205, v75
	v_sub_f32_e32 v75, v78, v191
	v_add_f32_e32 v74, v202, v224
	v_exp_f32_e32 v208, v75
	v_sub_f32_e32 v75, v79, v191
	v_add_f32_e32 v74, v203, v74
	v_exp_f32_e32 v209, v75
	v_sub_f32_e32 v75, v80, v191
	v_add_f32_e32 v74, v204, v74
	v_exp_f32_e32 v210, v75
	v_sub_f32_e32 v75, v81, v191
	v_add_f32_e32 v74, v205, v74
	v_exp_f32_e32 v211, v75
	v_add_f32_e32 v74, v208, v74
	v_add_f32_e32 v74, v209, v74
	v_add_f32_e32 v74, v210, v74
	v_add_f32_e32 v224, v211, v74
	v_exp_f32_e32 v194, v82
	v_exp_f32_e32 v195, v83
	v_sub_f32_e32 v83, v84, v191
	v_exp_f32_e32 v196, v83
	v_sub_f32_e32 v83, v85, v191
	v_exp_f32_e32 v197, v83
	v_sub_f32_e32 v83, v86, v191
	v_add_f32_e32 v82, v194, v224
	v_exp_f32_e32 v86, v83
	v_sub_f32_e32 v83, v87, v191
	v_add_f32_e32 v82, v195, v82
	v_exp_f32_e32 v87, v83
	v_sub_f32_e32 v83, v88, v191
	v_add_f32_e32 v82, v196, v82
	v_exp_f32_e32 v88, v83
	v_sub_f32_e32 v83, v89, v191
	v_add_f32_e32 v82, v197, v82
	v_exp_f32_e32 v89, v83
	v_add_f32_e32 v82, v86, v82
	v_add_f32_e32 v82, v87, v82
	v_add_f32_e32 v82, v88, v82
	v_add_f32_e32 v82, v89, v82
	v_add_u32_e32 v198, s21, v1
	v_sub_f32_e32 v66, v90, v191
	v_exp_f32_e32 v90, v66
	v_sub_f32_e32 v67, v91, v191
	v_exp_f32_e32 v91, v67
	v_sub_f32_e32 v67, v92, v191
	v_exp_f32_e32 v92, v67
	v_sub_f32_e32 v67, v93, v191
	v_exp_f32_e32 v93, v67
	v_sub_f32_e32 v67, v94, v191
	v_add_f32_e32 v66, v90, v82
	v_exp_f32_e32 v94, v67
	v_sub_f32_e32 v67, v95, v191
	v_add_f32_e32 v66, v91, v66
	v_exp_f32_e32 v95, v67
	v_sub_f32_e32 v67, v96, v191
	v_add_f32_e32 v66, v92, v66
	v_exp_f32_e32 v96, v67
	v_sub_f32_e32 v67, v97, v191
	v_add_f32_e32 v66, v93, v66
	v_exp_f32_e32 v97, v67
	v_add_f32_e32 v66, v94, v66
	v_add_f32_e32 v66, v95, v66
	v_add_f32_e32 v66, v96, v66
	v_add_f32_e32 v66, v97, v66
	v_add_f32_e32 v193, v193, v66
	v_add_u32_e32 v199, s21, v192
	ds_read_b64_tr_b16 v[66:67], v198 offset:0
	ds_read_b64_tr_b16 v[68:69], v199 offset:0x800
	ds_read_b64_tr_b16 v[70:71], v198 offset:0x1000
	ds_read_b64_tr_b16 v[72:73], v199 offset:0x1800
	ds_read_b64_tr_b16 v[74:75], v198 offset:0x2000
	ds_read_b64_tr_b16 v[76:77], v199 offset:0x2800
	ds_read_b64_tr_b16 v[78:79], v198 offset:0x3000
	ds_read_b64_tr_b16 v[80:81], v199 offset:0x3800
	s_branch .Lnsa_j3

; #define MFMA(a, b, c) __builtin_amdgcn_mfma_f32_32x32x16_f16((a), (b), (c), 0, 0, 0)
; #define QK_LD(dst, s0) do { dst[0] = *(const f16x8*)(Kst + kbe + 512 * ((s0) >> 1)); dst[1] = *(const f16x8*)(Kst + kbe + 512 * ((s0) >> 1) + 8192); \
;     dst[2] = *(const f16x8*)(Kst + kbo + 512 * ((s0) >> 1)); dst[3] = *(const f16x8*)(Kst + kbo + 512 * ((s0) >> 1) + 8192); } while (0)
; #define QK_LD(dst, s0) do { dst[0] = *(const f16x8*)(Kst + kbe + 512 * ((s0) >> 1)); dst[1] = *(const f16x8*)(Kst + kbe + 512 * ((s0) >> 1) + 8192); \
;     dst[2] = *(const f16x8*)(Kst + kbo + 512 * ((s0) >> 1)); dst[3] = *(const f16x8*)(Kst + kbo + 512 * ((s0) >> 1) + 8192); } while (0)
; #define EXP8(c, b0) do { _Pragma("unroll") for (int j_ = 0; j_ < 8; ++j_) { c[(b0) + j_] = fexp2(c[(b0) + j_] - me); s_ += c[(b0) + j_]; } } while (0)
; DI void qk_exp(f32x16& n0, f32x16& n1, const char* Kst, const f16x8 (&qf)[8], unsigned kbe, unsigned kbo, f32x16& c0, f32x16& c1, float me, float& ps) {
;   const f32x16 zero = {0.f, 0.f, 0.f, 0.f, 0.f, 0.f, 0.f, 0.f, 0.f, 0.f, 0.f, 0.f, 0.f, 0.f, 0.f, 0.f};
;   f16x8 ka[4], kb[4];
;     ...
;   float s_ = 0.f;
;   QK_LD(ka, 0);
;   n0 = MFMA(ka[0], qf[0], zero); n1 = MFMA(ka[1], qf[0], zero); n0 = MFMA(ka[2], qf[1], n0); n1 = MFMA(ka[3], qf[1], n1);
;   QK_LD(kb, 2);
;   EXP8(c0, 0);
;   n0 = MFMA(kb[0], qf[2], n0); n1 = MFMA(kb[1], qf[2], n1); n0 = MFMA(kb[2], qf[3], n0); n1 = MFMA(kb[3], qf[3], n1);
;   QK_LD(ka, 4);
;   EXP8(c0, 8);
;   n0 = MFMA(ka[0], qf[4], n0); n1 = MFMA(ka[1], qf[4], n1); n0 = MFMA(ka[2], qf[5], n0); n1 = MFMA(ka[3], qf[5], n1);
;   QK_LD(kb, 6);
;   EXP8(c1, 0);
;   n0 = MFMA(kb[0], qf[6], n0); n1 = MFMA(kb[1], qf[6], n1); n0 = MFMA(kb[2], qf[7], n0); n1 = MFMA(kb[3], qf[7], n1);
;   EXP8(c1, 8);
;   ps = s_;
;     ...
; }
.LBB0_718:
	s_lshl_b32 s0, s19, 15
	s_and_b32 s19, s0, 0x18000
	v_sub_f32_e32 v66, v66, v191
	s_cmp_lg_u32 s101, 0
	s_cbranch_scc1 .Lnsa_b3
	s_waitcnt lgkmcnt(0)
	v_mfma_f32_32x32x16_f16 v[114:129], v[98:101], v[150:153], 0
	v_exp_f32_e32 v214, v66
	v_sub_f32_e32 v67, v67, v191
	v_exp_f32_e32 v215, v67
	v_sub_f32_e32 v67, v68, v191
	v_exp_f32_e32 v216, v67
	v_sub_f32_e32 v67, v69, v191
	v_exp_f32_e32 v217, v67
	v_mfma_f32_32x32x16_f16 v[98:113], v[102:105], v[150:153], 0
	v_sub_f32_e32 v67, v70, v191
	v_add_f32_e32 v66, 0, v214
	v_exp_f32_e32 v218, v67
	v_sub_f32_e32 v67, v71, v191
	v_add_f32_e32 v66, v215, v66
	v_exp_f32_e32 v219, v67
	v_sub_f32_e32 v67, v72, v191
	v_mfma_f32_32x32x16_f16 v[114:129], v[194:197], v[158:161], v[114:129]
	v_add_f32_e32 v66, v216, v66
	v_exp_f32_e32 v220, v67
	v_sub_f32_e32 v67, v73, v191
	v_add_f32_e32 v66, v217, v66
	v_exp_f32_e32 v221, v67
	v_add_f32_e32 v66, v218, v66
	v_add_f32_e32 v66, v219, v66
	v_mfma_f32_32x32x16_f16 v[98:113], v[198:201], v[158:161], v[98:113]
	ds_read_b128 v[194:197], v212 offset:512
	ds_read_b128 v[198:201], v212 offset:8704
	ds_read_b128 v[202:205], v213 offset:512
	ds_read_b128 v[208:211], v213 offset:8704
	v_add_f32_e32 v66, v220, v66
	v_add_f32_e32 v224, v221, v66
	v_sub_f32_e32 v74, v74, v191
	v_sub_f32_e32 v75, v75, v191
	v_sub_f32_e32 v82, v82, v191
	v_sub_f32_e32 v83, v83, v191
	s_waitcnt lgkmcnt(0)
	v_mfma_f32_32x32x16_f16 v[114:129], v[194:197], v[142:145], v[114:129]
	s_lshl_b32 s0, s5, 15
	s_and_b32 s21, s0, 0x18000
	v_mfma_f32_32x32x16_f16 v[98:113], v[198:201], v[142:145], v[98:113]
	ds_read_b128 v[66:69], v212 offset:1024
	ds_read_b128 v[70:73], v212 offset:9216
	ds_read_b128 v[194:197], v213 offset:1024
	ds_read_b128 v[198:201], v213 offset:9216
	v_mfma_f32_32x32x16_f16 v[114:129], v[202:205], v[154:157], v[114:129]
	v_exp_f32_e32 v202, v74
	v_exp_f32_e32 v203, v75
	v_sub_f32_e32 v75, v76, v191
	v_exp_f32_e32 v204, v75
	v_sub_f32_e32 v75, v77, v191
	v_exp_f32_e32 v205, v75
	v_sub_f32_e32 v75, v78, v191
	v_mfma_f32_32x32x16_f16 v[98:113], v[208:211], v[154:157], v[98:113]
	v_add_f32_e32 v74, v202, v224
	v_exp_f32_e32 v208, v75
	v_sub_f32_e32 v75, v79, v191
	v_add_f32_e32 v74, v203, v74
	v_exp_f32_e32 v209, v75
	v_sub_f32_e32 v75, v80, v191
	v_add_f32_e32 v74, v204, v74
	s_waitcnt lgkmcnt(0)
	v_mfma_f32_32x32x16_f16 v[114:129], v[66:69], v[138:141], v[114:129]
	v_exp_f32_e32 v210, v75
	v_sub_f32_e32 v75, v81, v191
	v_add_f32_e32 v74, v205, v74
	v_exp_f32_e32 v211, v75
	v_add_f32_e32 v74, v208, v74
	v_add_f32_e32 v74, v209, v74
	v_add_f32_e32 v74, v210, v74
	v_mfma_f32_32x32x16_f16 v[98:113], v[70:73], v[138:141], v[98:113]
	v_add_f32_e32 v224, v211, v74
	ds_read_b128 v[66:69], v212 offset:1536
	ds_read_b128 v[70:73], v212 offset:9728
	ds_read_b128 v[74:77], v213 offset:1536
	ds_read_b128 v[78:81], v213 offset:9728
	v_mfma_f32_32x32x16_f16 v[114:129], v[194:197], v[146:149], v[114:129]
	v_exp_f32_e32 v194, v82
	v_exp_f32_e32 v195, v83
	v_sub_f32_e32 v83, v84, v191
	v_exp_f32_e32 v196, v83
	v_sub_f32_e32 v83, v85, v191
	v_exp_f32_e32 v197, v83
	v_sub_f32_e32 v83, v86, v191
	v_add_f32_e32 v82, v194, v224
	v_exp_f32_e32 v86, v83
	v_sub_f32_e32 v83, v87, v191
	v_add_f32_e32 v82, v195, v82
	v_exp_f32_e32 v87, v83
	v_sub_f32_e32 v83, v88, v191
	v_add_f32_e32 v82, v196, v82
	v_exp_f32_e32 v88, v83
	v_sub_f32_e32 v83, v89, v191
	v_mfma_f32_32x32x16_f16 v[98:113], v[198:201], v[146:149], v[98:113]
	v_add_f32_e32 v82, v197, v82
	v_exp_f32_e32 v89, v83
	v_add_f32_e32 v82, v86, v82
	v_add_f32_e32 v82, v87, v82
	v_add_f32_e32 v82, v88, v82
	v_add_f32_e32 v82, v89, v82
	v_add_u32_e32 v198, s21, v1
	s_waitcnt lgkmcnt(0)
	v_mfma_f32_32x32x16_f16 v[114:129], v[66:69], v[130:133], v[114:129]
	v_sub_f32_e32 v66, v90, v191
	v_exp_f32_e32 v90, v66
	v_sub_f32_e32 v67, v91, v191
	v_exp_f32_e32 v91, v67
	v_sub_f32_e32 v67, v92, v191
	v_exp_f32_e32 v92, v67
	v_sub_f32_e32 v67, v93, v191
	v_exp_f32_e32 v93, v67
	v_sub_f32_e32 v67, v94, v191
	v_add_f32_e32 v66, v90, v82
	v_exp_f32_e32 v94, v67
	v_sub_f32_e32 v67, v95, v191
	v_add_f32_e32 v66, v91, v66
	v_exp_f32_e32 v95, v67
	v_sub_f32_e32 v67, v96, v191
	v_add_f32_e32 v66, v92, v66
	v_exp_f32_e32 v96, v67
	v_sub_f32_e32 v67, v97, v191
	v_mfma_f32_32x32x16_f16 v[98:113], v[70:73], v[130:133], v[98:113]
	v_add_f32_e32 v66, v93, v66
	v_exp_f32_e32 v97, v67
	v_add_f32_e32 v66, v94, v66
	v_add_f32_e32 v66, v95, v66
	v_add_f32_e32 v66, v96, v66
	v_add_f32_e32 v66, v97, v66
	v_add_f32_e32 v193, v193, v66
	ds_read_b64_tr_b16 v[66:67], v198 offset:0
	v_add_u32_e32 v199, s21, v192
	ds_read_b64_tr_b16 v[68:69], v199 offset:0x800
	ds_read_b64_tr_b16 v[70:71], v198 offset:0x1000
	v_mfma_f32_32x32x16_f16 v[114:129], v[74:77], v[134:137], v[114:129]
	ds_read_b64_tr_b16 v[72:73], v199 offset:0x1800
	ds_read_b64_tr_b16 v[74:75], v198 offset:0x2000
	ds_read_b64_tr_b16 v[76:77], v199 offset:0x2800
	v_mfma_f32_32x32x16_f16 v[98:113], v[78:81], v[134:137], v[98:113]
	ds_read_b64_tr_b16 v[78:79], v198 offset:0x3000
	ds_read_b64_tr_b16 v[80:81], v199 offset:0x3800
; #define SBAR() __builtin_amdgcn_sched_barrier(0)
; DI float xhalf_max(float v) { auto rr = __builtin_amdgcn_permlane32_swap(__float_as_uint(v), __float_as_uint(v), false, false); return fmaxf(__uint_as_float(rr[0]), __uint_as_float(rr[1])); }
; DI float fexp2(float x) { return __builtin_amdgcn_exp2f(x); }
; DI void pv_max(f32x16 (&o)[4], unsigned vb0, unsigned vb1, const f32x16& p0, const f32x16& p1, const f32x16& n0, const f32x16& n1, float& pm) {
;   f16x8 pb[4]; pb[0] = pack8(p0, 0); pb[1] = pack8(p0, 1); pb[2] = pack8(p1, 0); pb[3] = pack8(p1, 1);
;   VFrag fa;
;   float mx = n0[0];
;   pv_rd<0>(fa, vb0, vb1);
;   asm volatile("s_waitcnt lgkmcnt(0)" ::: "memory"); SBAR();
;   pv_mm(o[0], fa, pb);
;   pv_rd<1>(fa, vb0, vb1);
; #pragma unroll
;   for (int r = 1; r < 8; ++r) mx = fmaxf(mx, n0[r]);
;   asm volatile("s_waitcnt lgkmcnt(0)" ::: "memory"); SBAR();
;   pv_mm(o[1], fa, pb);
;   pv_rd<2>(fa, vb0, vb1);
; #pragma unroll
;   for (int r = 8; r < 16; ++r) mx = fmaxf(mx, n0[r]);
;   asm volatile("s_waitcnt lgkmcnt(0)" ::: "memory"); SBAR();
;   pv_mm(o[2], fa, pb);
;   pv_rd<3>(fa, vb0, vb1);
; #pragma unroll
;   for (int r = 0; r < 8; ++r) mx = fmaxf(mx, n1[r]);
;   asm volatile("s_waitcnt lgkmcnt(0)" ::: "memory"); SBAR();
;   pv_mm(o[3], fa, pb);
; #pragma unroll
;   for (int r = 8; r < 16; ++r) mx = fmaxf(mx, n1[r]);
;   pm = mx;
; }
; DI float rowmax32(const f32x16& c0, const f32x16& c1) {
;   float pm = c0[0];
; #pragma unroll
;   for (int r = 1; r < 16; ++r) pm = fmaxf(pm, c0[r]);
; #pragma unroll
;   for (int r = 0; r < 16; ++r) pm = fmaxf(pm, c1[r]);
;   return xhalf_max(pm);
; }
; DI void osm_decide(float pmn, float& m, float& l, f32x16 (&o)[4]) {
;   if (!__all(pmn - m <= THR)) {
;     float mn = fmaxf(m, pmn); float alpha = fexp2(m - mn); m = mn; l *= alpha;
; #pragma unroll
;     for (int d = 0; d < 4; ++d)
; #pragma unroll
;       for (int r = 0; r < 16; ++r) o[d][r] *= alpha;
;   }
; }
.Lnsa_j3:
	s_waitcnt lgkmcnt(0)
	v_cvt_pk_f16_f32 v85, v220, v221
	v_cvt_pk_f16_f32 v84, v218, v219
	v_cvt_pk_f16_f32 v83, v216, v217
	v_cvt_pk_f16_f32 v82, v214, v215
	s_nop 1
	v_mfma_f32_32x32x16_f16 v[50:65], v[66:69], v[82:85], v[50:65]
	v_cvt_pk_f16_f32 v69, v210, v211
	v_cvt_pk_f16_f32 v68, v208, v209
	v_cvt_pk_f16_f32 v67, v204, v205
	v_cvt_pk_f16_f32 v66, v202, v203
	s_nop 1
	v_mfma_f32_32x32x16_f16 v[50:65], v[70:73], v[66:69], v[50:65]
	v_cvt_pk_f16_f32 v73, v88, v89
	v_cvt_pk_f16_f32 v72, v86, v87
	v_cvt_pk_f16_f32 v71, v196, v197
	v_cvt_pk_f16_f32 v70, v194, v195
	v_max_f32_e32 v194, v115, v115
	v_max_f32_e32 v195, v114, v114
	v_max_f32_e32 v194, v195, v194
	v_mfma_f32_32x32x16_f16 v[50:65], v[74:77], v[70:73], v[50:65]
	v_cvt_pk_f16_f32 v77, v96, v97
	v_cvt_pk_f16_f32 v76, v94, v95
	v_cvt_pk_f16_f32 v75, v92, v93
	v_cvt_pk_f16_f32 v74, v90, v91
	v_max3_f32 v194, v194, v116, v117
	v_max3_f32 v194, v194, v118, v119
	v_max3_f32 v194, v194, v120, v121
	v_mfma_f32_32x32x16_f16 v[50:65], v[78:81], v[74:77], v[50:65]
	ds_read_b64_tr_b16 v[78:79], v198 offset:0x200
	ds_read_b64_tr_b16 v[80:81], v199 offset:0xa00
	ds_read_b64_tr_b16 v[86:87], v198 offset:0x1200
	ds_read_b64_tr_b16 v[88:89], v199 offset:0x1a00
	ds_read_b64_tr_b16 v[90:91], v198 offset:0x2200
	ds_read_b64_tr_b16 v[92:93], v199 offset:0x2a00
	ds_read_b64_tr_b16 v[94:95], v198 offset:0x3200
	ds_read_b64_tr_b16 v[96:97], v199 offset:0x3a00
	s_waitcnt lgkmcnt(0)
	s_nop 0
	v_mfma_f32_32x32x16_f16 v[34:49], v[78:81], v[82:85], v[34:49]
	ds_read_b64_tr_b16 v[78:79], v198 offset:0x400
	ds_read_b64_tr_b16 v[80:81], v199 offset:0xc00
	v_max3_f32 v194, v194, v122, v123
	v_max3_f32 v194, v194, v124, v125
	v_max3_f32 v194, v194, v126, v127
	v_max3_f32 v194, v194, v128, v129
	v_mfma_f32_32x32x16_f16 v[34:49], v[86:89], v[66:69], v[34:49]
	ds_read_b64_tr_b16 v[86:87], v198 offset:0x1400
	ds_read_b64_tr_b16 v[88:89], v199 offset:0x1c00
	v_mfma_f32_32x32x16_f16 v[34:49], v[90:93], v[70:73], v[34:49]
	ds_read_b64_tr_b16 v[90:91], v198 offset:0x2400
	ds_read_b64_tr_b16 v[92:93], v199 offset:0x2c00
	v_mfma_f32_32x32x16_f16 v[34:49], v[94:97], v[74:77], v[34:49]
	ds_read_b64_tr_b16 v[94:95], v198 offset:0x3400
	ds_read_b64_tr_b16 v[96:97], v199 offset:0x3c00
	s_waitcnt lgkmcnt(0)
	v_mfma_f32_32x32x16_f16 v[18:33], v[78:81], v[82:85], v[18:33]
	ds_read_b64_tr_b16 v[78:79], v198 offset:0x600
	ds_read_b64_tr_b16 v[80:81], v199 offset:0xe00
	v_max3_f32 v194, v194, v98, v99
	v_max3_f32 v194, v194, v100, v101
	v_max3_f32 v194, v194, v102, v103
	v_max3_f32 v194, v194, v104, v105
	v_mfma_f32_32x32x16_f16 v[18:33], v[86:89], v[66:69], v[18:33]
	ds_read_b64_tr_b16 v[86:87], v198 offset:0x1600
	ds_read_b64_tr_b16 v[88:89], v199 offset:0x1e00
	v_mfma_f32_32x32x16_f16 v[18:33], v[90:93], v[70:73], v[18:33]
	ds_read_b64_tr_b16 v[90:91], v198 offset:0x2600
	ds_read_b64_tr_b16 v[92:93], v199 offset:0x2e00
	v_mfma_f32_32x32x16_f16 v[18:33], v[94:97], v[74:77], v[18:33]
	ds_read_b64_tr_b16 v[94:95], v198 offset:0x3600
	ds_read_b64_tr_b16 v[96:97], v199 offset:0x3e00
	s_waitcnt lgkmcnt(0)
	v_mfma_f32_32x32x16_f16 v[2:17], v[78:81], v[82:85], v[2:17]
	v_mfma_f32_32x32x16_f16 v[2:17], v[86:89], v[66:69], v[2:17]
	v_max3_f32 v66, v194, v106, v107
	v_max3_f32 v66, v66, v108, v109
	v_max3_f32 v66, v66, v110, v111
	v_max3_f32 v66, v66, v112, v113
	v_mov_b32_e32 v67, v66
	s_nop 1
	v_permlane32_swap_b32_e32 v66, v67
	v_mfma_f32_32x32x16_f16 v[2:17], v[90:93], v[70:73], v[2:17]
	v_max_f32_e32 v67, v67, v67
	v_max_f32_e32 v66, v66, v66
	v_max_f32_e32 v66, v66, v67
	v_sub_f32_e32 v67, v66, v191
	v_cmp_ge_f32_e32 vcc, s73, v67
	s_cmp_eq_u64 vcc, exec
	v_mfma_f32_32x32x16_f16 v[2:17], v[94:97], v[74:77], v[2:17]
	s_cbranch_scc1 .LBB0_720
	v_max_f32_e32 v66, v66, v66
	v_max_f32_e32 v67, v191, v191
	v_max_f32_e32 v67, v67, v66
	v_sub_f32_e32 v66, v191, v67
	v_exp_f32_e32 v66, v66
	v_mov_b32_e32 v191, v67
	v_mul_f32_e32 v193, v193, v66
	v_pk_mul_f32 v[64:65], v[64:65], v[66:67] op_sel_hi:[1,0]
	v_pk_mul_f32 v[62:63], v[62:63], v[66:67] op_sel_hi:[1,0]
	v_pk_mul_f32 v[60:61], v[60:61], v[66:67] op_sel_hi:[1,0]
	v_pk_mul_f32 v[58:59], v[58:59], v[66:67] op_sel_hi:[1,0]
	v_pk_mul_f32 v[56:57], v[56:57], v[66:67] op_sel_hi:[1,0]
	v_pk_mul_f32 v[54:55], v[54:55], v[66:67] op_sel_hi:[1,0]
	v_pk_mul_f32 v[52:53], v[52:53], v[66:67] op_sel_hi:[1,0]
	v_pk_mul_f32 v[50:51], v[50:51], v[66:67] op_sel_hi:[1,0]
	v_pk_mul_f32 v[48:49], v[48:49], v[66:67] op_sel_hi:[1,0]
	v_pk_mul_f32 v[46:47], v[46:47], v[66:67] op_sel_hi:[1,0]
	v_pk_mul_f32 v[44:45], v[44:45], v[66:67] op_sel_hi:[1,0]
	v_pk_mul_f32 v[42:43], v[42:43], v[66:67] op_sel_hi:[1,0]
	v_pk_mul_f32 v[40:41], v[40:41], v[66:67] op_sel_hi:[1,0]
	v_pk_mul_f32 v[38:39], v[38:39], v[66:67] op_sel_hi:[1,0]
	v_pk_mul_f32 v[36:37], v[36:37], v[66:67] op_sel_hi:[1,0]
	v_pk_mul_f32 v[34:35], v[34:35], v[66:67] op_sel_hi:[1,0]
	v_pk_mul_f32 v[32:33], v[32:33], v[66:67] op_sel_hi:[1,0]
	v_pk_mul_f32 v[30:31], v[30:31], v[66:67] op_sel_hi:[1,0]
	v_pk_mul_f32 v[28:29], v[28:29], v[66:67] op_sel_hi:[1,0]
	v_pk_mul_f32 v[26:27], v[26:27], v[66:67] op_sel_hi:[1,0]
	v_pk_mul_f32 v[24:25], v[24:25], v[66:67] op_sel_hi:[1,0]
	v_pk_mul_f32 v[22:23], v[22:23], v[66:67] op_sel_hi:[1,0]
	v_pk_mul_f32 v[20:21], v[20:21], v[66:67] op_sel_hi:[1,0]
	v_pk_mul_f32 v[18:19], v[18:19], v[66:67] op_sel_hi:[1,0]
	v_pk_mul_f32 v[16:17], v[16:17], v[66:67] op_sel_hi:[1,0]
	v_pk_mul_f32 v[14:15], v[14:15], v[66:67] op_sel_hi:[1,0]
	v_pk_mul_f32 v[12:13], v[12:13], v[66:67] op_sel_hi:[1,0]
	v_pk_mul_f32 v[10:11], v[10:11], v[66:67] op_sel_hi:[1,0]
	v_pk_mul_f32 v[8:9], v[8:9], v[66:67] op_sel_hi:[1,0]
	v_pk_mul_f32 v[6:7], v[6:7], v[66:67] op_sel_hi:[1,0]
	v_pk_mul_f32 v[4:5], v[4:5], v[66:67] op_sel_hi:[1,0]
	v_pk_mul_f32 v[2:3], v[2:3], v[66:67] op_sel_hi:[1,0]

; #define MFMA(a, b, c) __builtin_amdgcn_mfma_f32_32x32x16_f16((a), (b), (c), 0, 0, 0)
; #define QK_LD(dst, s0) do { dst[0] = *(const f16x8*)(Kst + kbe + 512 * ((s0) >> 1)); dst[1] = *(const f16x8*)(Kst + kbe + 512 * ((s0) >> 1) + 8192); \
;     dst[2] = *(const f16x8*)(Kst + kbo + 512 * ((s0) >> 1)); dst[3] = *(const f16x8*)(Kst + kbo + 512 * ((s0) >> 1) + 8192); } while (0)
; #define QK_LD(dst, s0) do { dst[0] = *(const f16x8*)(Kst + kbe + 512 * ((s0) >> 1)); dst[1] = *(const f16x8*)(Kst + kbe + 512 * ((s0) >> 1) + 8192); \
;     dst[2] = *(const f16x8*)(Kst + kbo + 512 * ((s0) >> 1)); dst[3] = *(const f16x8*)(Kst + kbo + 512 * ((s0) >> 1) + 8192); } while (0)
; #define EXP8(c, b0) do { _Pragma("unroll") for (int j_ = 0; j_ < 8; ++j_) { c[(b0) + j_] = fexp2(c[(b0) + j_] - me); s_ += c[(b0) + j_]; } } while (0)
; DI void qk_exp(f32x16& n0, f32x16& n1, const char* Kst, const f16x8 (&qf)[8], unsigned kbe, unsigned kbo, f32x16& c0, f32x16& c1, float me, float& ps) {
;   const f32x16 zero = {0.f, 0.f, 0.f, 0.f, 0.f, 0.f, 0.f, 0.f, 0.f, 0.f, 0.f, 0.f, 0.f, 0.f, 0.f, 0.f};
;   f16x8 ka[4], kb[4];
;     ...
;   float s_ = 0.f;
;   QK_LD(ka, 0);
;   n0 = MFMA(ka[0], qf[0], zero); n1 = MFMA(ka[1], qf[0], zero); n0 = MFMA(ka[2], qf[1], n0); n1 = MFMA(ka[3], qf[1], n1);
;   QK_LD(kb, 2);
;   EXP8(c0, 0);
;   n0 = MFMA(kb[0], qf[2], n0); n1 = MFMA(kb[1], qf[2], n1); n0 = MFMA(kb[2], qf[3], n0); n1 = MFMA(kb[3], qf[3], n1);
;   QK_LD(ka, 4);
;   EXP8(c0, 8);
;   n0 = MFMA(ka[0], qf[4], n0); n1 = MFMA(ka[1], qf[4], n1); n0 = MFMA(ka[2], qf[5], n0); n1 = MFMA(ka[3], qf[5], n1);
;   QK_LD(kb, 6);
;   EXP8(c1, 0);
;   n0 = MFMA(kb[0], qf[6], n0); n1 = MFMA(kb[1], qf[6], n1); n0 = MFMA(kb[2], qf[7], n0); n1 = MFMA(kb[3], qf[7], n1);
;   EXP8(c1, 8);
;   ps = s_;
;     ...
; }
.Lnsa_b4:
	ds_read_b128 v[240:243], v212 offset:512
	ds_read_b128 v[244:247], v212 offset:8704
	ds_read_b128 v[202:205], v213 offset:512
	ds_read_b128 v[208:211], v213 offset:8704
	s_waitcnt lgkmcnt(4)
	v_mfma_f32_32x32x16_f16 v[66:81], v[66:69], v[150:153], 0
	v_mfma_f32_32x32x16_f16 v[82:97], v[82:85], v[150:153], 0
	v_mfma_f32_32x32x16_f16 v[66:81], v[194:197], v[158:161], v[66:81]
	v_mfma_f32_32x32x16_f16 v[82:97], v[198:201], v[158:161], v[82:97]
	ds_read_b128 v[248:251], v212 offset:1024
	ds_read_b128 v[214:217], v212 offset:9216
	ds_read_b128 v[194:197], v213 offset:1024
	ds_read_b128 v[198:201], v213 offset:9216
	s_waitcnt lgkmcnt(4)
	v_mfma_f32_32x32x16_f16 v[66:81], v[240:243], v[142:145], v[66:81]
	v_mfma_f32_32x32x16_f16 v[82:97], v[244:247], v[142:145], v[82:97]
	v_mfma_f32_32x32x16_f16 v[66:81], v[202:205], v[154:157], v[66:81]
	v_mfma_f32_32x32x16_f16 v[82:97], v[208:211], v[154:157], v[82:97]
	ds_read_b128 v[240:243], v212 offset:1536
	ds_read_b128 v[244:247], v212 offset:9728
	ds_read_b128 v[202:205], v213 offset:1536
	ds_read_b128 v[208:211], v213 offset:9728
	s_waitcnt lgkmcnt(4)
	v_mfma_f32_32x32x16_f16 v[66:81], v[248:251], v[138:141], v[66:81]
	v_mfma_f32_32x32x16_f16 v[82:97], v[214:217], v[138:141], v[82:97]
	v_mfma_f32_32x32x16_f16 v[66:81], v[194:197], v[146:149], v[66:81]
	v_mfma_f32_32x32x16_f16 v[82:97], v[198:201], v[146:149], v[82:97]
	s_waitcnt lgkmcnt(0)
	v_mfma_f32_32x32x16_f16 v[66:81], v[240:243], v[130:133], v[66:81]
	v_mfma_f32_32x32x16_f16 v[82:97], v[244:247], v[130:133], v[82:97]
	v_mfma_f32_32x32x16_f16 v[66:81], v[202:205], v[134:137], v[66:81]
	v_mfma_f32_32x32x16_f16 v[82:97], v[208:211], v[134:137], v[82:97]
	v_exp_f32_e32 v214, v114
	v_sub_f32_e32 v115, v115, v191
	v_exp_f32_e32 v215, v115
	v_sub_f32_e32 v115, v116, v191
	v_exp_f32_e32 v216, v115
	v_sub_f32_e32 v115, v117, v191
	v_exp_f32_e32 v217, v115
	v_sub_f32_e32 v115, v118, v191
	v_add_f32_e32 v114, 0, v214
	v_exp_f32_e32 v218, v115
	v_sub_f32_e32 v115, v119, v191
	v_add_f32_e32 v114, v215, v114
	v_exp_f32_e32 v219, v115
	v_sub_f32_e32 v115, v120, v191
	v_add_f32_e32 v114, v216, v114
	v_exp_f32_e32 v220, v115
	v_sub_f32_e32 v115, v121, v191
	v_add_f32_e32 v114, v217, v114
	v_exp_f32_e32 v221, v115
	v_add_f32_e32 v114, v218, v114
	v_add_f32_e32 v114, v219, v114
	v_add_f32_e32 v114, v220, v114
	v_add_f32_e32 v224, v221, v114
	v_sub_f32_e32 v122, v122, v191
	v_sub_f32_e32 v123, v123, v191
	v_sub_f32_e32 v98, v98, v191
	v_sub_f32_e32 v99, v99, v191
	v_exp_f32_e32 v202, v122
	v_exp_f32_e32 v203, v123
	v_sub_f32_e32 v123, v124, v191
	v_exp_f32_e32 v204, v123
	v_sub_f32_e32 v123, v125, v191
	v_exp_f32_e32 v205, v123
	v_sub_f32_e32 v123, v126, v191
	v_add_f32_e32 v122, v202, v224
	v_exp_f32_e32 v208, v123
	v_sub_f32_e32 v123, v127, v191
	v_add_f32_e32 v122, v203, v122
	v_exp_f32_e32 v209, v123
	v_sub_f32_e32 v123, v128, v191
	v_add_f32_e32 v122, v204, v122
	v_exp_f32_e32 v210, v123
	v_sub_f32_e32 v123, v129, v191
	v_add_f32_e32 v122, v205, v122
	v_exp_f32_e32 v211, v123
	v_add_f32_e32 v122, v208, v122
	v_add_f32_e32 v122, v209, v122
	v_add_f32_e32 v122, v210, v122
	v_add_f32_e32 v224, v211, v122
	v_add_u32_e32 v212, s19, v1
	v_add_u32_e32 v213, s19, v192
	v_exp_f32_e32 v194, v98
	v_exp_f32_e32 v195, v99
	v_sub_f32_e32 v99, v100, v191
	v_exp_f32_e32 v196, v99
	v_sub_f32_e32 v99, v101, v191
	v_exp_f32_e32 v197, v99
	v_sub_f32_e32 v99, v102, v191
	v_add_f32_e32 v98, v194, v224
	v_exp_f32_e32 v198, v99
	v_sub_f32_e32 v99, v103, v191
	v_add_f32_e32 v98, v195, v98
	v_exp_f32_e32 v199, v99
	v_sub_f32_e32 v99, v104, v191
	v_add_f32_e32 v98, v196, v98
	v_exp_f32_e32 v200, v99
	v_sub_f32_e32 v99, v105, v191
	v_add_f32_e32 v98, v197, v98
	v_exp_f32_e32 v201, v99
	v_sub_f32_e32 v99, v106, v191
	v_add_f32_e32 v98, v198, v98
	v_add_f32_e32 v98, v199, v98
	v_exp_f32_e32 v118, v99
	v_sub_f32_e32 v99, v107, v191
	v_exp_f32_e32 v119, v99
	v_sub_f32_e32 v99, v108, v191
	v_add_f32_e32 v98, v200, v98
	v_exp_f32_e32 v120, v99
	v_sub_f32_e32 v99, v109, v191
	v_add_f32_e32 v98, v201, v98
	v_exp_f32_e32 v121, v99
	v_sub_f32_e32 v99, v110, v191
	v_add_f32_e32 v98, v118, v98
	v_exp_f32_e32 v122, v99
	v_sub_f32_e32 v99, v111, v191
	v_add_f32_e32 v98, v119, v98
	v_exp_f32_e32 v123, v99
	v_sub_f32_e32 v99, v112, v191
	v_add_f32_e32 v98, v120, v98
	v_exp_f32_e32 v124, v99
	v_sub_f32_e32 v99, v113, v191
	v_add_f32_e32 v98, v121, v98
	v_exp_f32_e32 v125, v99
	v_add_f32_e32 v98, v122, v98
	v_add_f32_e32 v98, v123, v98
	v_add_f32_e32 v98, v124, v98
	v_add_f32_e32 v98, v125, v98
	v_add_f32_e32 v193, v193, v98
	ds_read_b64_tr_b16 v[98:99], v212 offset:0
	ds_read_b64_tr_b16 v[100:101], v213 offset:0x800
	ds_read_b64_tr_b16 v[102:103], v212 offset:0x1000
	ds_read_b64_tr_b16 v[104:105], v213 offset:0x1800
	ds_read_b64_tr_b16 v[106:107], v212 offset:0x2000
	ds_read_b64_tr_b16 v[108:109], v213 offset:0x2800
	ds_read_b64_tr_b16 v[110:111], v212 offset:0x3000
	ds_read_b64_tr_b16 v[112:113], v213 offset:0x3800
	s_branch .Lnsa_j4

; #define MFMA(a, b, c) __builtin_amdgcn_mfma_f32_32x32x16_f16((a), (b), (c), 0, 0, 0)
; #define QK_LD(dst, s0) do { dst[0] = *(const f16x8*)(Kst + kbe + 512 * ((s0) >> 1)); dst[1] = *(const f16x8*)(Kst + kbe + 512 * ((s0) >> 1) + 8192); \
;     dst[2] = *(const f16x8*)(Kst + kbo + 512 * ((s0) >> 1)); dst[3] = *(const f16x8*)(Kst + kbo + 512 * ((s0) >> 1) + 8192); } while (0)
; #define QK_LD(dst, s0) do { dst[0] = *(const f16x8*)(Kst + kbe + 512 * ((s0) >> 1)); dst[1] = *(const f16x8*)(Kst + kbe + 512 * ((s0) >> 1) + 8192); \
;     dst[2] = *(const f16x8*)(Kst + kbo + 512 * ((s0) >> 1)); dst[3] = *(const f16x8*)(Kst + kbo + 512 * ((s0) >> 1) + 8192); } while (0)
; #define EXP8(c, b0) do { _Pragma("unroll") for (int j_ = 0; j_ < 8; ++j_) { c[(b0) + j_] = fexp2(c[(b0) + j_] - me); s_ += c[(b0) + j_]; } } while (0)
; DI void qk_exp(f32x16& n0, f32x16& n1, const char* Kst, const f16x8 (&qf)[8], unsigned kbe, unsigned kbo, f32x16& c0, f32x16& c1, float me, float& ps) {
;   const f32x16 zero = {0.f, 0.f, 0.f, 0.f, 0.f, 0.f, 0.f, 0.f, 0.f, 0.f, 0.f, 0.f, 0.f, 0.f, 0.f, 0.f};
;   f16x8 ka[4], kb[4];
;     ...
;   float s_ = 0.f;
;   QK_LD(ka, 0);
;   n0 = MFMA(ka[0], qf[0], zero); n1 = MFMA(ka[1], qf[0], zero); n0 = MFMA(ka[2], qf[1], n0); n1 = MFMA(ka[3], qf[1], n1);
;   QK_LD(kb, 2);
;   EXP8(c0, 0);
;   n0 = MFMA(kb[0], qf[2], n0); n1 = MFMA(kb[1], qf[2], n1); n0 = MFMA(kb[2], qf[3], n0); n1 = MFMA(kb[3], qf[3], n1);
;   QK_LD(ka, 4);
;   EXP8(c0, 8);
;   n0 = MFMA(ka[0], qf[4], n0); n1 = MFMA(ka[1], qf[4], n1); n0 = MFMA(ka[2], qf[5], n0); n1 = MFMA(ka[3], qf[5], n1);
;   QK_LD(kb, 6);
;   EXP8(c1, 0);
;   n0 = MFMA(kb[0], qf[6], n0); n1 = MFMA(kb[1], qf[6], n1); n0 = MFMA(kb[2], qf[7], n0); n1 = MFMA(kb[3], qf[7], n1);
;   EXP8(c1, 8);
;   ps = s_;
;     ...
; }
.LBB0_743:
	v_sub_f32_e32 v114, v114, v191
	s_cmp_lg_u32 s101, 0
	s_cbranch_scc1 .Lnsa_b4
	s_waitcnt lgkmcnt(0)
	v_mfma_f32_32x32x16_f16 v[66:81], v[66:69], v[150:153], 0
	v_exp_f32_e32 v214, v114
	v_sub_f32_e32 v115, v115, v191
	v_exp_f32_e32 v215, v115
	v_sub_f32_e32 v115, v116, v191
	v_exp_f32_e32 v216, v115
	v_sub_f32_e32 v115, v117, v191
	v_exp_f32_e32 v217, v115
	v_mfma_f32_32x32x16_f16 v[82:97], v[82:85], v[150:153], 0
	v_sub_f32_e32 v115, v118, v191
	v_add_f32_e32 v114, 0, v214
	v_exp_f32_e32 v218, v115
	v_sub_f32_e32 v115, v119, v191
	v_add_f32_e32 v114, v215, v114
	v_exp_f32_e32 v219, v115
	v_sub_f32_e32 v115, v120, v191
	v_mfma_f32_32x32x16_f16 v[66:81], v[194:197], v[158:161], v[66:81]
	v_add_f32_e32 v114, v216, v114
	v_exp_f32_e32 v220, v115
	v_sub_f32_e32 v115, v121, v191
	v_add_f32_e32 v114, v217, v114
	v_exp_f32_e32 v221, v115
	v_add_f32_e32 v114, v218, v114
	v_add_f32_e32 v114, v219, v114
	v_mfma_f32_32x32x16_f16 v[82:97], v[198:201], v[158:161], v[82:97]
	ds_read_b128 v[194:197], v212 offset:512
	ds_read_b128 v[198:201], v212 offset:8704
	ds_read_b128 v[202:205], v213 offset:512
	ds_read_b128 v[208:211], v213 offset:8704
	v_add_f32_e32 v114, v220, v114
	v_add_f32_e32 v224, v221, v114
	v_sub_f32_e32 v122, v122, v191
	v_sub_f32_e32 v123, v123, v191
	v_sub_f32_e32 v98, v98, v191
	v_sub_f32_e32 v99, v99, v191
	s_waitcnt lgkmcnt(0)
	v_mfma_f32_32x32x16_f16 v[66:81], v[194:197], v[142:145], v[66:81]
	v_mfma_f32_32x32x16_f16 v[82:97], v[198:201], v[142:145], v[82:97]
	ds_read_b128 v[114:117], v212 offset:1024
	ds_read_b128 v[118:121], v212 offset:9216
	ds_read_b128 v[194:197], v213 offset:1024
	ds_read_b128 v[198:201], v213 offset:9216
	v_mfma_f32_32x32x16_f16 v[66:81], v[202:205], v[154:157], v[66:81]
	v_exp_f32_e32 v202, v122
	v_exp_f32_e32 v203, v123
	v_sub_f32_e32 v123, v124, v191
	v_exp_f32_e32 v204, v123
	v_sub_f32_e32 v123, v125, v191
	v_exp_f32_e32 v205, v123
	v_sub_f32_e32 v123, v126, v191
	v_mfma_f32_32x32x16_f16 v[82:97], v[208:211], v[154:157], v[82:97]
	v_add_f32_e32 v122, v202, v224
	v_exp_f32_e32 v208, v123
	v_sub_f32_e32 v123, v127, v191
	v_add_f32_e32 v122, v203, v122
	v_exp_f32_e32 v209, v123
	v_sub_f32_e32 v123, v128, v191
	v_add_f32_e32 v122, v204, v122
	s_waitcnt lgkmcnt(0)
	v_mfma_f32_32x32x16_f16 v[66:81], v[114:117], v[138:141], v[66:81]
	v_exp_f32_e32 v210, v123
	v_sub_f32_e32 v123, v129, v191
	v_add_f32_e32 v122, v205, v122
	v_exp_f32_e32 v211, v123
	v_add_f32_e32 v122, v208, v122
	v_add_f32_e32 v122, v209, v122
	v_add_f32_e32 v122, v210, v122
	v_mfma_f32_32x32x16_f16 v[82:97], v[118:121], v[138:141], v[82:97]
	v_add_f32_e32 v224, v211, v122
	ds_read_b128 v[114:117], v212 offset:1536
	ds_read_b128 v[118:121], v212 offset:9728
	ds_read_b128 v[122:125], v213 offset:1536
	ds_read_b128 v[126:129], v213 offset:9728
	v_add_u32_e32 v212, s19, v1
	v_add_u32_e32 v213, s19, v192
	v_mfma_f32_32x32x16_f16 v[66:81], v[194:197], v[146:149], v[66:81]
	v_exp_f32_e32 v194, v98
	v_exp_f32_e32 v195, v99
	v_sub_f32_e32 v99, v100, v191
	v_exp_f32_e32 v196, v99
	v_sub_f32_e32 v99, v101, v191
	v_exp_f32_e32 v197, v99
	v_sub_f32_e32 v99, v102, v191
	v_mfma_f32_32x32x16_f16 v[82:97], v[198:201], v[146:149], v[82:97]
	v_add_f32_e32 v98, v194, v224
	v_exp_f32_e32 v198, v99
	v_sub_f32_e32 v99, v103, v191
	v_add_f32_e32 v98, v195, v98
	v_exp_f32_e32 v199, v99
	v_sub_f32_e32 v99, v104, v191
	v_add_f32_e32 v98, v196, v98
	s_waitcnt lgkmcnt(0)
	v_mfma_f32_32x32x16_f16 v[66:81], v[114:117], v[130:133], v[66:81]
	v_exp_f32_e32 v200, v99
	v_sub_f32_e32 v99, v105, v191
	v_add_f32_e32 v98, v197, v98
	v_exp_f32_e32 v201, v99
	v_sub_f32_e32 v99, v106, v191
	v_add_f32_e32 v98, v198, v98
	v_add_f32_e32 v98, v199, v98
	v_mfma_f32_32x32x16_f16 v[82:97], v[118:121], v[130:133], v[82:97]
	v_exp_f32_e32 v118, v99
	v_sub_f32_e32 v99, v107, v191
	v_exp_f32_e32 v119, v99
	v_sub_f32_e32 v99, v108, v191
	v_add_f32_e32 v98, v200, v98
	v_exp_f32_e32 v120, v99
	v_sub_f32_e32 v99, v109, v191
	v_add_f32_e32 v98, v201, v98
	v_exp_f32_e32 v121, v99
	v_sub_f32_e32 v99, v110, v191
	v_mfma_f32_32x32x16_f16 v[66:81], v[122:125], v[134:137], v[66:81]
	v_add_f32_e32 v98, v118, v98
	v_exp_f32_e32 v122, v99
	v_sub_f32_e32 v99, v111, v191
	v_add_f32_e32 v98, v119, v98
	v_exp_f32_e32 v123, v99
	v_sub_f32_e32 v99, v112, v191
	v_add_f32_e32 v98, v120, v98
	v_exp_f32_e32 v124, v99
	v_sub_f32_e32 v99, v113, v191
	v_add_f32_e32 v98, v121, v98
	v_exp_f32_e32 v125, v99
	v_add_f32_e32 v98, v122, v98
	v_add_f32_e32 v98, v123, v98
	v_add_f32_e32 v98, v124, v98
	v_add_f32_e32 v98, v125, v98
	v_add_f32_e32 v193, v193, v98
	ds_read_b64_tr_b16 v[98:99], v212 offset:0
	ds_read_b64_tr_b16 v[100:101], v213 offset:0x800
	ds_read_b64_tr_b16 v[102:103], v212 offset:0x1000
	v_mfma_f32_32x32x16_f16 v[82:97], v[126:129], v[134:137], v[82:97]
	ds_read_b64_tr_b16 v[104:105], v213 offset:0x1800
	ds_read_b64_tr_b16 v[106:107], v212 offset:0x2000
	ds_read_b64_tr_b16 v[108:109], v213 offset:0x2800
	ds_read_b64_tr_b16 v[110:111], v212 offset:0x3000
	ds_read_b64_tr_b16 v[112:113], v213 offset:0x3800
; #define SBAR() __builtin_amdgcn_sched_barrier(0)
; DI float xhalf_max(float v) { auto rr = __builtin_amdgcn_permlane32_swap(__float_as_uint(v), __float_as_uint(v), false, false); return fmaxf(__uint_as_float(rr[0]), __uint_as_float(rr[1])); }
; DI float fexp2(float x) { return __builtin_amdgcn_exp2f(x); }
; DI void pv_max(f32x16 (&o)[4], unsigned vb0, unsigned vb1, const f32x16& p0, const f32x16& p1, const f32x16& n0, const f32x16& n1, float& pm) {
;   f16x8 pb[4]; pb[0] = pack8(p0, 0); pb[1] = pack8(p0, 1); pb[2] = pack8(p1, 0); pb[3] = pack8(p1, 1);
;   VFrag fa;
;   float mx = n0[0];
;   pv_rd<0>(fa, vb0, vb1);
;   asm volatile("s_waitcnt lgkmcnt(0)" ::: "memory"); SBAR();
;   pv_mm(o[0], fa, pb);
;   pv_rd<1>(fa, vb0, vb1);
; #pragma unroll
;   for (int r = 1; r < 8; ++r) mx = fmaxf(mx, n0[r]);
;   asm volatile("s_waitcnt lgkmcnt(0)" ::: "memory"); SBAR();
;   pv_mm(o[1], fa, pb);
;   pv_rd<2>(fa, vb0, vb1);
; #pragma unroll
;   for (int r = 8; r < 16; ++r) mx = fmaxf(mx, n0[r]);
;   asm volatile("s_waitcnt lgkmcnt(0)" ::: "memory"); SBAR();
;   pv_mm(o[2], fa, pb);
;   pv_rd<3>(fa, vb0, vb1);
; #pragma unroll
;   for (int r = 0; r < 8; ++r) mx = fmaxf(mx, n1[r]);
;   asm volatile("s_waitcnt lgkmcnt(0)" ::: "memory"); SBAR();
;   pv_mm(o[3], fa, pb);
; #pragma unroll
;   for (int r = 8; r < 16; ++r) mx = fmaxf(mx, n1[r]);
;   pm = mx;
; }
; DI float rowmax32(const f32x16& c0, const f32x16& c1) {
;   float pm = c0[0];
; #pragma unroll
;   for (int r = 1; r < 16; ++r) pm = fmaxf(pm, c0[r]);
; #pragma unroll
;   for (int r = 0; r < 16; ++r) pm = fmaxf(pm, c1[r]);
;   return xhalf_max(pm);
; }
; DI void osm_decide(float pmn, float& m, float& l, f32x16 (&o)[4]) {
;   if (!__all(pmn - m <= THR)) {
;     float mn = fmaxf(m, pmn); float alpha = fexp2(m - mn); m = mn; l *= alpha;
; #pragma unroll
;     for (int d = 0; d < 4; ++d)
; #pragma unroll
;       for (int r = 0; r < 16; ++r) o[d][r] *= alpha;
;   }
; }
.Lnsa_j4:
	s_waitcnt lgkmcnt(0)
	v_cvt_pk_f16_f32 v117, v220, v221
	v_cvt_pk_f16_f32 v116, v218, v219
	v_cvt_pk_f16_f32 v115, v216, v217
	v_cvt_pk_f16_f32 v114, v214, v215
	s_nop 1
	v_mfma_f32_32x32x16_f16 v[50:65], v[98:101], v[114:117], v[50:65]
	v_cvt_pk_f16_f32 v101, v210, v211
	v_cvt_pk_f16_f32 v100, v208, v209
	v_cvt_pk_f16_f32 v99, v204, v205
	v_cvt_pk_f16_f32 v98, v202, v203
	s_nop 1
	v_mfma_f32_32x32x16_f16 v[50:65], v[102:105], v[98:101], v[50:65]
	v_cvt_pk_f16_f32 v105, v200, v201
	v_cvt_pk_f16_f32 v104, v198, v199
	v_cvt_pk_f16_f32 v103, v196, v197
	v_cvt_pk_f16_f32 v102, v194, v195
	v_max_f32_e32 v194, v67, v67
	v_max_f32_e32 v195, v66, v66
	v_max_f32_e32 v194, v195, v194
	v_mfma_f32_32x32x16_f16 v[50:65], v[106:109], v[102:105], v[50:65]
	v_cvt_pk_f16_f32 v109, v124, v125
	v_cvt_pk_f16_f32 v108, v122, v123
	v_cvt_pk_f16_f32 v107, v120, v121
	v_cvt_pk_f16_f32 v106, v118, v119
	v_max3_f32 v194, v194, v68, v69
	v_max3_f32 v194, v194, v70, v71
	v_max3_f32 v194, v194, v72, v73
	v_mfma_f32_32x32x16_f16 v[50:65], v[110:113], v[106:109], v[50:65]
	ds_read_b64_tr_b16 v[110:111], v212 offset:0x200
	ds_read_b64_tr_b16 v[112:113], v213 offset:0xa00
	ds_read_b64_tr_b16 v[118:119], v212 offset:0x1200
	ds_read_b64_tr_b16 v[120:121], v213 offset:0x1a00
	ds_read_b64_tr_b16 v[122:123], v212 offset:0x2200
	ds_read_b64_tr_b16 v[124:125], v213 offset:0x2a00
	ds_read_b64_tr_b16 v[126:127], v212 offset:0x3200
	ds_read_b64_tr_b16 v[128:129], v213 offset:0x3a00
	s_waitcnt lgkmcnt(0)
	s_nop 0
	v_mfma_f32_32x32x16_f16 v[34:49], v[110:113], v[114:117], v[34:49]
	ds_read_b64_tr_b16 v[110:111], v212 offset:0x400
	ds_read_b64_tr_b16 v[112:113], v213 offset:0xc00
	v_max3_f32 v194, v194, v74, v75
	v_max3_f32 v194, v194, v76, v77
	v_max3_f32 v194, v194, v78, v79
	v_max3_f32 v194, v194, v80, v81
	v_mfma_f32_32x32x16_f16 v[34:49], v[118:121], v[98:101], v[34:49]
	ds_read_b64_tr_b16 v[118:119], v212 offset:0x1400
	ds_read_b64_tr_b16 v[120:121], v213 offset:0x1c00
	v_mfma_f32_32x32x16_f16 v[34:49], v[122:125], v[102:105], v[34:49]
	ds_read_b64_tr_b16 v[122:123], v212 offset:0x2400
	ds_read_b64_tr_b16 v[124:125], v213 offset:0x2c00
	v_mfma_f32_32x32x16_f16 v[34:49], v[126:129], v[106:109], v[34:49]
	ds_read_b64_tr_b16 v[126:127], v212 offset:0x3400
	ds_read_b64_tr_b16 v[128:129], v213 offset:0x3c00
	s_waitcnt lgkmcnt(0)
	v_mfma_f32_32x32x16_f16 v[18:33], v[110:113], v[114:117], v[18:33]
	ds_read_b64_tr_b16 v[110:111], v212 offset:0x600
	ds_read_b64_tr_b16 v[112:113], v213 offset:0xe00
	v_max3_f32 v194, v194, v82, v83
	v_max3_f32 v194, v194, v84, v85
	v_max3_f32 v194, v194, v86, v87
	v_max3_f32 v194, v194, v88, v89
	v_mfma_f32_32x32x16_f16 v[18:33], v[118:121], v[98:101], v[18:33]
	ds_read_b64_tr_b16 v[118:119], v212 offset:0x1600
	ds_read_b64_tr_b16 v[120:121], v213 offset:0x1e00
	v_mfma_f32_32x32x16_f16 v[18:33], v[122:125], v[102:105], v[18:33]
	ds_read_b64_tr_b16 v[122:123], v212 offset:0x2600
	ds_read_b64_tr_b16 v[124:125], v213 offset:0x2e00
	v_mfma_f32_32x32x16_f16 v[18:33], v[126:129], v[106:109], v[18:33]
	ds_read_b64_tr_b16 v[126:127], v212 offset:0x3600
	ds_read_b64_tr_b16 v[128:129], v213 offset:0x3e00
	s_waitcnt lgkmcnt(0)
	v_mfma_f32_32x32x16_f16 v[2:17], v[110:113], v[114:117], v[2:17]
	v_mfma_f32_32x32x16_f16 v[2:17], v[118:121], v[98:101], v[2:17]
	v_max3_f32 v98, v194, v90, v91
	v_max3_f32 v98, v98, v92, v93
	v_max3_f32 v98, v98, v94, v95
	v_max3_f32 v98, v98, v96, v97
	v_mov_b32_e32 v99, v98
	s_nop 1
	v_permlane32_swap_b32_e32 v98, v99
	v_mfma_f32_32x32x16_f16 v[2:17], v[122:125], v[102:105], v[2:17]
	v_max_f32_e32 v99, v99, v99
	v_max_f32_e32 v98, v98, v98
	v_max_f32_e32 v98, v98, v99
	v_sub_f32_e32 v99, v98, v191
	v_cmp_ge_f32_e32 vcc, s73, v99
	s_cmp_eq_u64 vcc, exec
	v_mfma_f32_32x32x16_f16 v[2:17], v[126:129], v[106:109], v[2:17]
	s_cbranch_scc1 .LBB0_694
	v_max_f32_e32 v98, v98, v98
	v_max_f32_e32 v99, v191, v191
	v_max_f32_e32 v99, v99, v98
	v_sub_f32_e32 v98, v191, v99
	v_exp_f32_e32 v98, v98
	v_mov_b32_e32 v191, v99
	v_mul_f32_e32 v193, v193, v98
	v_pk_mul_f32 v[64:65], v[64:65], v[98:99] op_sel_hi:[1,0]
	v_pk_mul_f32 v[62:63], v[62:63], v[98:99] op_sel_hi:[1,0]
	v_pk_mul_f32 v[60:61], v[60:61], v[98:99] op_sel_hi:[1,0]
	v_pk_mul_f32 v[58:59], v[58:59], v[98:99] op_sel_hi:[1,0]
	v_pk_mul_f32 v[56:57], v[56:57], v[98:99] op_sel_hi:[1,0]
	v_pk_mul_f32 v[54:55], v[54:55], v[98:99] op_sel_hi:[1,0]
	v_pk_mul_f32 v[52:53], v[52:53], v[98:99] op_sel_hi:[1,0]
	v_pk_mul_f32 v[50:51], v[50:51], v[98:99] op_sel_hi:[1,0]
	v_pk_mul_f32 v[48:49], v[48:49], v[98:99] op_sel_hi:[1,0]
	v_pk_mul_f32 v[46:47], v[46:47], v[98:99] op_sel_hi:[1,0]
	v_pk_mul_f32 v[44:45], v[44:45], v[98:99] op_sel_hi:[1,0]
	v_pk_mul_f32 v[42:43], v[42:43], v[98:99] op_sel_hi:[1,0]
	v_pk_mul_f32 v[40:41], v[40:41], v[98:99] op_sel_hi:[1,0]
	v_pk_mul_f32 v[38:39], v[38:39], v[98:99] op_sel_hi:[1,0]
	v_pk_mul_f32 v[36:37], v[36:37], v[98:99] op_sel_hi:[1,0]
	v_pk_mul_f32 v[34:35], v[34:35], v[98:99] op_sel_hi:[1,0]
	v_pk_mul_f32 v[32:33], v[32:33], v[98:99] op_sel_hi:[1,0]
	v_pk_mul_f32 v[30:31], v[30:31], v[98:99] op_sel_hi:[1,0]
	v_pk_mul_f32 v[28:29], v[28:29], v[98:99] op_sel_hi:[1,0]
	v_pk_mul_f32 v[26:27], v[26:27], v[98:99] op_sel_hi:[1,0]
	v_pk_mul_f32 v[24:25], v[24:25], v[98:99] op_sel_hi:[1,0]
	v_pk_mul_f32 v[22:23], v[22:23], v[98:99] op_sel_hi:[1,0]
	v_pk_mul_f32 v[20:21], v[20:21], v[98:99] op_sel_hi:[1,0]
	v_pk_mul_f32 v[18:19], v[18:19], v[98:99] op_sel_hi:[1,0]
	v_pk_mul_f32 v[16:17], v[16:17], v[98:99] op_sel_hi:[1,0]
	v_pk_mul_f32 v[14:15], v[14:15], v[98:99] op_sel_hi:[1,0]
	v_pk_mul_f32 v[12:13], v[12:13], v[98:99] op_sel_hi:[1,0]
	v_pk_mul_f32 v[10:11], v[10:11], v[98:99] op_sel_hi:[1,0]
	v_pk_mul_f32 v[8:9], v[8:9], v[98:99] op_sel_hi:[1,0]
	v_pk_mul_f32 v[6:7], v[6:7], v[98:99] op_sel_hi:[1,0]
	v_pk_mul_f32 v[4:5], v[4:5], v[98:99] op_sel_hi:[1,0]
	v_pk_mul_f32 v[2:3], v[2:3], v[98:99] op_sel_hi:[1,0]
	s_branch .LBB0_694

; #define LAS __attribute__((address_space(3)))
; DI void xcd_barrier(const XcdBarrier& b) { xcd_barrier(b, XbNone()); }
; template <int PH>
; __global__ void __launch_bounds__(512, 2) hybrid_kernel(Params p) {
;   __shared__ __attribute__((aligned(16))) char smem[LDS_BYTES];
;   if (PH == -1) {
;     unsigned* bar = (unsigned*)(p.ws + WS_BAR);
;     volatile LAS unsigned* xst = (volatile LAS unsigned*)(smem + LDS_IMG);
;     if (threadIdx.x == 0) { xst[0] = 0u; xst[1] = 0u; }
;     __syncthreads();
;     XcdBarrier xb = xcd_barrier_post(bar, xst);
;     phase_prep(p, smem); xcd_barrier(xb);
;     phase_gemm1(p, smem); xcd_barrier(xb);
;     phase_attn(p, smem, 0, ATTN_UNITS, 0); xcd_barrier(xb);
;     phase_gemm2(p, smem);
;     FinPre fp;
; #pragma unroll
;     for (int i = 0; i < 4; ++i) fp.x0[i] = (f32x4){0.f, 0.f, 0.f, 0.f};
;     xcd_barrier(xb, [&]() { fin_prefetch(p, fp); });
;     phase_final<true>(p, fp);
;   } else {
;     if (PH == 0) phase_prep(p, smem);
;     if (PH == 1) phase_gemm1(p, smem);
;     if (PH == 3) phase_attn(p, smem, 0, ATTN_UNITS, 0);
;     if (PH == 4) phase_gemm2(p, smem);
;     if (PH == 5) { FinPre fp; phase_final<false>(p, fp); }
;   }
; }
	.amdhsa_kernel _Z13hybrid_kernelILin1EEv6Params
		.amdhsa_group_segment_fixed_size 147520
		.amdhsa_private_segment_fixed_size 0
		.amdhsa_kernarg_size 408
		.amdhsa_user_sgpr_count 2
		.amdhsa_user_sgpr_dispatch_ptr 0
		.amdhsa_user_sgpr_queue_ptr 0
		.amdhsa_user_sgpr_kernarg_segment_ptr 1
		.amdhsa_user_sgpr_dispatch_id 0
		.amdhsa_user_sgpr_kernarg_preload_length 0
		.amdhsa_user_sgpr_kernarg_preload_offset 0
		.amdhsa_user_sgpr_private_segment_size 0
		.amdhsa_uses_dynamic_stack 0
		.amdhsa_enable_private_segment 0
		.amdhsa_system_sgpr_workgroup_id_x 1
		.amdhsa_system_sgpr_workgroup_id_y 0
		.amdhsa_system_sgpr_workgroup_id_z 0
		.amdhsa_system_sgpr_workgroup_info 0
		.amdhsa_system_vgpr_workitem_id 0
		.amdhsa_next_free_vgpr 256
		.amdhsa_next_free_sgpr 102
		.amdhsa_accum_offset 256
		.amdhsa_reserve_vcc 1
		.amdhsa_float_round_mode_32 0
		.amdhsa_float_round_mode_16_64 0
		.amdhsa_float_denorm_mode_32 3
		.amdhsa_float_denorm_mode_16_64 3
		.amdhsa_dx10_clamp 1
		.amdhsa_ieee_mode 1
		.amdhsa_fp16_overflow 0
		.amdhsa_tg_split 0
		.amdhsa_exception_fp_ieee_invalid_op 0
		.amdhsa_exception_fp_denorm_src 0
		.amdhsa_exception_fp_ieee_div_zero 0
		.amdhsa_exception_fp_ieee_overflow 0
		.amdhsa_exception_fp_ieee_underflow 0
		.amdhsa_exception_fp_ieee_inexact 0
		.amdhsa_exception_int_div_zero 0
	.end_amdhsa_kernel

; #define LAS __attribute__((address_space(3)))
; DI void xcd_barrier(const XcdBarrier& b) { xcd_barrier(b, XbNone()); }
; template <int PH>
; __global__ void __launch_bounds__(512, 2) hybrid_kernel(Params p) {
;   __shared__ __attribute__((aligned(16))) char smem[LDS_BYTES];
;   if (PH == -1) {
;     unsigned* bar = (unsigned*)(p.ws + WS_BAR);
;     volatile LAS unsigned* xst = (volatile LAS unsigned*)(smem + LDS_IMG);
;     if (threadIdx.x == 0) { xst[0] = 0u; xst[1] = 0u; }
;     __syncthreads();
;     XcdBarrier xb = xcd_barrier_post(bar, xst);
;     phase_prep(p, smem); xcd_barrier(xb);
;     phase_gemm1(p, smem); xcd_barrier(xb);
;     phase_attn(p, smem, 0, ATTN_UNITS, 0); xcd_barrier(xb);
;     phase_gemm2(p, smem);
;     FinPre fp;
; #pragma unroll
;     for (int i = 0; i < 4; ++i) fp.x0[i] = (f32x4){0.f, 0.f, 0.f, 0.f};
;     xcd_barrier(xb, [&]() { fin_prefetch(p, fp); });
;     phase_final<true>(p, fp);
;   } else {
;     if (PH == 0) phase_prep(p, smem);
;     if (PH == 1) phase_gemm1(p, smem);
;     if (PH == 3) phase_attn(p, smem, 0, ATTN_UNITS, 0);
;     if (PH == 4) phase_gemm2(p, smem);
;     if (PH == 5) { FinPre fp; phase_final<false>(p, fp); }
;   }
; }
amdhsa.kernels:
  - .agpr_count:     0
    .args:
      - .offset:         0
        .size:           152
        .value_kind:     by_value
      - .offset:         152
        .size:           4
        .value_kind:     hidden_block_count_x
      - .offset:         156
        .size:           4
        .value_kind:     hidden_block_count_y
      - .offset:         160
        .size:           4
        .value_kind:     hidden_block_count_z
      - .offset:         164
        .size:           2
        .value_kind:     hidden_group_size_x
      - .offset:         166
        .size:           2
        .value_kind:     hidden_group_size_y
      - .offset:         168
        .size:           2
        .value_kind:     hidden_group_size_z
      - .offset:         170
        .size:           2
        .value_kind:     hidden_remainder_x
      - .offset:         172
        .size:           2
        .value_kind:     hidden_remainder_y
      - .offset:         174
        .size:           2
        .value_kind:     hidden_remainder_z
      - .offset:         192
        .size:           8
        .value_kind:     hidden_global_offset_x
      - .offset:         200
        .size:           8
        .value_kind:     hidden_global_offset_y
      - .offset:         208
        .size:           8
        .value_kind:     hidden_global_offset_z
      - .offset:         216
        .size:           2
        .value_kind:     hidden_grid_dims
    .group_segment_fixed_size: 147520
    .kernarg_segment_align: 8
    .kernarg_segment_size: 408
    .language:       OpenCL C
    .language_version:
      - 2
      - 0
    .max_flat_workgroup_size: 512
    .name:           _Z13hybrid_kernelILin1EEv6Params
    .private_segment_fixed_size: 0
    .sgpr_count:     108
    .sgpr_spill_count: 42
    .symbol:         _Z13hybrid_kernelILin1EEv6Params.kd
    .uniform_work_group_size: 1
    .uses_dynamic_stack: false
    .vgpr_count:     256
    .vgpr_spill_count: 0
    .wavefront_size: 64
